# attention tile loop: one static s_setprio 1 for waves 4-7 before the loop, s_setprio 0 at the unit epilogue
# speedup vs baseline: 1.0091x; 1.0091x over previous
.LBB0_557:
	s_setprio 0
	s_or_b64 exec, exec, s[4:5]
	s_waitcnt lgkmcnt(0)
	s_barrier
	v_and_b32_e32 v129, 63, v181
	v_lshrrev_b32_e32 v130, 6, v181
	v_lshrrev_b32_e32 v131, 5, v129
	v_and_b32_e32 v132, 31, v129
	v_lshlrev_b32_e32 v128, 13, v130
	v_lshl_add_u32 v128, v131, 10, v128
	v_lshl_add_u32 v128, v132, 1, v128
	v_add_u32_e32 v72, v169, v176
	ds_read_b128 v[64:67], v72
	ds_read_b128 v[68:71], v72 offset:32
	s_lshl_b32 s44, s11, 1
	v_lshlrev_b32_e32 v176, 1, v168
	s_add_i32 s9, s9, s8
	s_waitcnt lgkmcnt(1)
	v_rcp_f32_e32 v73, v64
	v_rcp_f32_e32 v74, v65
	v_rcp_f32_e32 v75, v66
	v_rcp_f32_e32 v76, v67
	ds_read_b128 v[64:67], v72 offset:64
	s_waitcnt lgkmcnt(1)
	v_rcp_f32_e32 v77, v68
	v_rcp_f32_e32 v78, v69
	v_rcp_f32_e32 v79, v70
	v_rcp_f32_e32 v80, v71
	ds_read_b128 v[68:71], v72 offset:96
	s_waitcnt lgkmcnt(1)
	v_rcp_f32_e32 v72, v64
	v_rcp_f32_e32 v81, v65
	v_mov_b64_e32 v[64:65], s[60:61]
	v_mad_i64_i32 v[64:65], s[2:3], v170, s87, v[64:65]
	v_lshl_add_u64 v[64:65], v[64:65], 0, s[44:45]
	v_lshl_add_u64 v[64:65], v[64:65], 0, v[176:177]
	v_mul_u32_u24_e32 v176, 0x3000, v159
	v_mul_f32_e32 v0, v0, v73
	v_lshl_add_u64 v[64:65], v[64:65], 0, v[176:177]
	v_cvt_pk_bf16_f32 v0, v0, v177
	ds_write_b16 v128, v0
	v_mul_f32_e32 v0, v32, v73
	v_cvt_pk_bf16_f32 v0, v0, v177
	ds_write_b16 v128, v0 offset:64
	v_mul_f32_e32 v0, v16, v73
	v_cvt_pk_bf16_f32 v0, v0, v177
	ds_write_b16 v128, v0 offset:128
	v_mul_f32_e32 v0, v48, v73
	v_cvt_pk_bf16_f32 v0, v0, v177
	ds_write_b16 v128, v0 offset:192
	v_mul_f32_e32 v0, v1, v74
	v_cvt_pk_bf16_f32 v0, v0, v177
	ds_write_b16 v128, v0 offset:256
	v_mul_f32_e32 v0, v33, v74
	v_cvt_pk_bf16_f32 v0, v0, v177
	ds_write_b16 v128, v0 offset:320
	v_mul_f32_e32 v0, v17, v74
	v_cvt_pk_bf16_f32 v0, v0, v177
	ds_write_b16 v128, v0 offset:384
	v_mul_f32_e32 v0, v49, v74
	v_cvt_pk_bf16_f32 v0, v0, v177
	ds_write_b16 v128, v0 offset:448
	v_mul_f32_e32 v0, v2, v75
	s_movk_i32 s2, 0x1000
	v_cvt_pk_bf16_f32 v2, v0, v177
	v_add_co_u32_e32 v0, vcc, s2, v64
	s_movk_i32 s2, 0x2000
	s_nop 0
	v_addc_co_u32_e32 v1, vcc, 0, v65, vcc
	ds_write_b16 v128, v2 offset:512
	v_mul_f32_e32 v2, v34, v75
	v_cvt_pk_bf16_f32 v2, v2, v177
	ds_write_b16 v128, v2 offset:576
	v_mul_f32_e32 v2, v18, v75
	v_cvt_pk_bf16_f32 v2, v2, v177
	ds_write_b16 v128, v2 offset:640
	v_mul_f32_e32 v2, v50, v75
	v_cvt_pk_bf16_f32 v2, v2, v177
	ds_write_b16 v128, v2 offset:704
	v_mul_f32_e32 v0, v3, v76
	v_cvt_pk_bf16_f32 v2, v0, v177
	v_add_co_u32_e32 v0, vcc, s2, v64
	s_movk_i32 s2, 0x6000
	s_nop 0
	v_addc_co_u32_e32 v1, vcc, 0, v65, vcc
	ds_write_b16 v128, v2 offset:768
	v_mul_f32_e32 v2, v35, v76
	v_cvt_pk_bf16_f32 v2, v2, v177
	ds_write_b16 v128, v2 offset:832
	v_mul_f32_e32 v2, v19, v76
	v_cvt_pk_bf16_f32 v2, v2, v177
	ds_write_b16 v128, v2 offset:896
	v_mul_f32_e32 v2, v51, v76
	v_cvt_pk_bf16_f32 v2, v2, v177
	ds_write_b16 v128, v2 offset:960
	v_mul_f32_e32 v0, v4, v77
	v_cvt_pk_bf16_f32 v2, v0, v177
	v_add_co_u32_e32 v0, vcc, s2, v64
	s_movk_i32 s2, 0x7000
	s_nop 0
	v_addc_co_u32_e32 v1, vcc, 0, v65, vcc
	ds_write_b16 v128, v2 offset:2048
	v_mul_f32_e32 v2, v36, v77
	v_cvt_pk_bf16_f32 v2, v2, v177
	ds_write_b16 v128, v2 offset:2112
	v_mul_f32_e32 v2, v20, v77
	v_cvt_pk_bf16_f32 v2, v2, v177
	ds_write_b16 v128, v2 offset:2176
	v_mul_f32_e32 v2, v52, v77
	v_cvt_pk_bf16_f32 v2, v2, v177
	ds_write_b16 v128, v2 offset:2240
	v_mul_f32_e32 v2, v5, v78
	v_cvt_pk_bf16_f32 v2, v2, v177
	ds_write_b16 v128, v2 offset:2304
	v_mul_f32_e32 v2, v37, v78
	v_cvt_pk_bf16_f32 v2, v2, v177
	ds_write_b16 v128, v2 offset:2368
	v_mul_f32_e32 v2, v21, v78
	v_cvt_pk_bf16_f32 v2, v2, v177
	ds_write_b16 v128, v2 offset:2432
	v_mul_f32_e32 v2, v53, v78
	v_cvt_pk_bf16_f32 v2, v2, v177
	ds_write_b16 v128, v2 offset:2496
	v_mul_f32_e32 v0, v6, v79
	v_cvt_pk_bf16_f32 v2, v0, v177
	v_add_co_u32_e32 v0, vcc, s2, v64
	s_mov_b32 s2, 0xc000
	s_nop 0
	v_addc_co_u32_e32 v1, vcc, 0, v65, vcc
	ds_write_b16 v128, v2 offset:2560
	v_mul_f32_e32 v2, v38, v79
	v_cvt_pk_bf16_f32 v2, v2, v177
	ds_write_b16 v128, v2 offset:2624
	v_mul_f32_e32 v2, v22, v79
	v_cvt_pk_bf16_f32 v2, v2, v177
	ds_write_b16 v128, v2 offset:2688
	v_mul_f32_e32 v2, v54, v79
	v_cvt_pk_bf16_f32 v2, v2, v177
	ds_write_b16 v128, v2 offset:2752
	v_mul_f32_e32 v0, v7, v80
	v_cvt_pk_bf16_f32 v2, v0, v177
	v_add_co_u32_e32 v0, vcc, s84, v64
	v_rcp_f32_e32 v66, v66
	s_nop 0
	v_addc_co_u32_e32 v1, vcc, 0, v65, vcc
	ds_write_b16 v128, v2 offset:2816
	v_mul_f32_e32 v2, v39, v80
	v_cvt_pk_bf16_f32 v2, v2, v177
	ds_write_b16 v128, v2 offset:2880
	v_mul_f32_e32 v2, v23, v80
	v_cvt_pk_bf16_f32 v2, v2, v177
	ds_write_b16 v128, v2 offset:2944
	v_mul_f32_e32 v2, v55, v80
	v_cvt_pk_bf16_f32 v2, v2, v177
	ds_write_b16 v128, v2 offset:3008
	v_mul_f32_e32 v0, v8, v72
	v_cvt_pk_bf16_f32 v2, v0, v177
	v_add_co_u32_e32 v0, vcc, s2, v64
	s_mov_b32 s2, 0xd000
	s_nop 0
	v_addc_co_u32_e32 v1, vcc, 0, v65, vcc
	ds_write_b16 v128, v2 offset:4096
	v_mul_f32_e32 v2, v40, v72
	v_cvt_pk_bf16_f32 v2, v2, v177
	ds_write_b16 v128, v2 offset:4160
	v_mul_f32_e32 v2, v24, v72
	v_cvt_pk_bf16_f32 v2, v2, v177
	ds_write_b16 v128, v2 offset:4224
	v_mul_f32_e32 v2, v56, v72
	v_cvt_pk_bf16_f32 v2, v2, v177
	ds_write_b16 v128, v2 offset:4288
	v_mul_f32_e32 v2, v9, v81
	v_cvt_pk_bf16_f32 v2, v2, v177
	ds_write_b16 v128, v2 offset:4352
	v_mul_f32_e32 v2, v41, v81
	v_cvt_pk_bf16_f32 v2, v2, v177
	ds_write_b16 v128, v2 offset:4416
	v_mul_f32_e32 v2, v25, v81
	v_cvt_pk_bf16_f32 v2, v2, v177
	ds_write_b16 v128, v2 offset:4480
	v_mul_f32_e32 v2, v57, v81
	v_cvt_pk_bf16_f32 v2, v2, v177
	ds_write_b16 v128, v2 offset:4544
	v_mul_f32_e32 v0, v10, v66
	v_cvt_pk_bf16_f32 v2, v0, v177
	v_add_co_u32_e32 v0, vcc, s2, v64
	v_rcp_f32_e32 v67, v67
	s_nop 0
	v_addc_co_u32_e32 v1, vcc, 0, v65, vcc
	ds_write_b16 v128, v2 offset:4608
	v_mul_f32_e32 v2, v42, v66
	v_cvt_pk_bf16_f32 v2, v2, v177
	ds_write_b16 v128, v2 offset:4672
	v_mul_f32_e32 v2, v26, v66
	v_cvt_pk_bf16_f32 v2, v2, v177
	ds_write_b16 v128, v2 offset:4736
	v_mul_f32_e32 v2, v58, v66
	v_cvt_pk_bf16_f32 v2, v2, v177
	ds_write_b16 v128, v2 offset:4800
	v_mul_f32_e32 v0, v11, v67
	s_mov_b32 s2, 0xe000
	v_cvt_pk_bf16_f32 v2, v0, v177
	v_add_co_u32_e32 v0, vcc, s2, v64
	s_waitcnt lgkmcnt(0)
	v_rcp_f32_e32 v68, v68
	v_addc_co_u32_e32 v1, vcc, 0, v65, vcc
	ds_write_b16 v128, v2 offset:4864
	v_mul_f32_e32 v2, v43, v67
	v_cvt_pk_bf16_f32 v2, v2, v177
	ds_write_b16 v128, v2 offset:4928
	v_mul_f32_e32 v2, v27, v67
	v_cvt_pk_bf16_f32 v2, v2, v177
	ds_write_b16 v128, v2 offset:4992
	v_mul_f32_e32 v2, v59, v67
	v_cvt_pk_bf16_f32 v2, v2, v177
	ds_write_b16 v128, v2 offset:5056
	v_mul_f32_e32 v0, v12, v68
	s_mov_b32 s2, 0x12000
	v_cvt_pk_bf16_f32 v2, v0, v177
	v_add_co_u32_e32 v0, vcc, s2, v64
	v_rcp_f32_e32 v69, v69
	s_nop 0
	v_addc_co_u32_e32 v1, vcc, 0, v65, vcc
	ds_write_b16 v128, v2 offset:6144
	v_mul_f32_e32 v2, v44, v68
	v_cvt_pk_bf16_f32 v2, v2, v177
	ds_write_b16 v128, v2 offset:6208
	v_mul_f32_e32 v2, v28, v68
	v_cvt_pk_bf16_f32 v2, v2, v177
	ds_write_b16 v128, v2 offset:6272
	v_mul_f32_e32 v2, v60, v68
	v_cvt_pk_bf16_f32 v2, v2, v177
	ds_write_b16 v128, v2 offset:6336
	v_mul_f32_e32 v2, v13, v69
	v_cvt_pk_bf16_f32 v2, v2, v177
	ds_write_b16 v128, v2 offset:6400
	v_mul_f32_e32 v2, v45, v69
	v_rcp_f32_e32 v70, v70
	v_cvt_pk_bf16_f32 v2, v2, v177
	ds_write_b16 v128, v2 offset:6464
	v_mul_f32_e32 v2, v29, v69
	v_cvt_pk_bf16_f32 v2, v2, v177
	ds_write_b16 v128, v2 offset:6528
	v_mul_f32_e32 v2, v61, v69
	v_cvt_pk_bf16_f32 v2, v2, v177
	ds_write_b16 v128, v2 offset:6592
	v_mul_f32_e32 v0, v14, v70
	s_mov_b32 s2, 0x13000
	v_cvt_pk_bf16_f32 v2, v0, v177
	v_add_co_u32_e32 v0, vcc, s2, v64
	v_rcp_f32_e32 v71, v71
	s_nop 0
	v_addc_co_u32_e32 v1, vcc, 0, v65, vcc
	ds_write_b16 v128, v2 offset:6656
	v_mul_f32_e32 v2, v46, v70
	v_cvt_pk_bf16_f32 v2, v2, v177
	ds_write_b16 v128, v2 offset:6720
	v_mul_f32_e32 v2, v30, v70
	v_cvt_pk_bf16_f32 v2, v2, v177
	ds_write_b16 v128, v2 offset:6784
	v_mul_f32_e32 v2, v62, v70
	v_cvt_pk_bf16_f32 v2, v2, v177
	ds_write_b16 v128, v2 offset:6848
	v_mul_f32_e32 v0, v15, v71
	s_mov_b32 s2, 0x14000
	v_cvt_pk_bf16_f32 v2, v0, v177
	v_add_co_u32_e32 v0, vcc, s2, v64
	s_cmp_ge_i32 s9, s10
	s_nop 0
	v_addc_co_u32_e32 v1, vcc, 0, v65, vcc
	ds_write_b16 v128, v2 offset:6912
	v_mul_f32_e32 v2, v47, v71
	v_cvt_pk_bf16_f32 v2, v2, v177
	ds_write_b16 v128, v2 offset:6976
	v_mul_f32_e32 v2, v31, v71
	v_cvt_pk_bf16_f32 v2, v2, v177
	ds_write_b16 v128, v2 offset:7040
	v_mul_f32_e32 v2, v63, v71
	v_cvt_pk_bf16_f32 v2, v2, v177
	ds_write_b16 v128, v2 offset:7104
	v_lshrrev_b32_e32 v133, 4, v129
	v_and_b32_e32 v134, 15, v129
	v_lshlrev_b32_e32 v135, 13, v130
	v_lshl_add_u32 v135, v133, 8, v135
	v_lshl_add_u32 v135, v134, 4, v135
	s_waitcnt lgkmcnt(0)
	ds_read_b128 v[182:185], v135
	ds_read_b128 v[186:189], v135 offset:1024
	ds_read_b128 v[190:193], v135 offset:2048
	ds_read_b128 v[194:197], v135 offset:3072
	ds_read_b128 v[198:201], v135 offset:4096
	ds_read_b128 v[202:205], v135 offset:5120
	ds_read_b128 v[206:209], v135 offset:6144
	ds_read_b128 v[210:213], v135 offset:7168
	v_mul_u32_u24_e32 v136, 0x3000, v131
	v_lshl_add_u32 v136, v132, 1, v136
	v_mov_b32_e32 v137, 0
	v_sub_co_u32_e32 v64, vcc, v64, v136
	s_nop 1
	v_subb_co_u32_e32 v65, vcc, v65, v137, vcc
	v_mul_u32_u24_e32 v136, 0xc00, v133
	v_lshl_add_u32 v136, v134, 4, v136
	v_lshl_add_u64 v[64:65], v[64:65], 0, v[136:137]
	s_mov_b64 s[6:7], 0x3000
	s_waitcnt lgkmcnt(7)
	global_store_dwordx4 v[64:65], v[182:185], off
	v_lshl_add_u64 v[64:65], v[64:65], 0, s[6:7]
	s_waitcnt lgkmcnt(6)
	global_store_dwordx4 v[64:65], v[186:189], off
	v_lshl_add_u64 v[64:65], v[64:65], 0, s[6:7]
	s_waitcnt lgkmcnt(5)
	global_store_dwordx4 v[64:65], v[190:193], off
	v_lshl_add_u64 v[64:65], v[64:65], 0, s[6:7]
	s_waitcnt lgkmcnt(4)
	global_store_dwordx4 v[64:65], v[194:197], off
	v_lshl_add_u64 v[64:65], v[64:65], 0, s[6:7]
	s_waitcnt lgkmcnt(3)
	global_store_dwordx4 v[64:65], v[198:201], off
	v_lshl_add_u64 v[64:65], v[64:65], 0, s[6:7]
	s_waitcnt lgkmcnt(2)
	global_store_dwordx4 v[64:65], v[202:205], off
	v_lshl_add_u64 v[64:65], v[64:65], 0, s[6:7]
	s_waitcnt lgkmcnt(1)
	global_store_dwordx4 v[64:65], v[206:209], off
	v_lshl_add_u64 v[64:65], v[64:65], 0, s[6:7]
	s_waitcnt lgkmcnt(0)
	global_store_dwordx4 v[64:65], v[210:213], off
	s_waitcnt vmcnt(63) expcnt(7) lgkmcnt(15)
	s_barrier
	s_cbranch_scc1 .LBB0_579

.LBB0_562:
	v_mov_b32_e32 v41, v181
	s_add_i32 s7, 0, 0x14000
	v_ashrrev_i32_e32 v0, 6, v41
	v_and_b32_e32 v1, 0x3fffffc0, v41
	s_and_b32 s5, s5, 7
	v_and_b32_e32 v168, 31, v41
	v_lshl_add_u32 v169, v1, 2, s7
	s_movk_i32 s7, 0x1800
	v_lshl_add_u32 v170, v0, 5, s6
	v_mul_lo_u32 v37, v0, s7
	v_add_u32_e32 v36, v170, v168
	v_mov_b64_e32 v[0:1], s[60:61]
	s_mul_i32 s11, s5, 0xc0
	v_bfe_u32 v159, v41, 5, 1
	v_mad_i64_i32 v[0:1], s[6:7], v36, s87, v[0:1]
	s_lshl_b32 s44, s11, 1
	v_lshl_add_u64 v[0:1], v[0:1], 0, s[44:45]
	v_lshlrev_b32_e32 v176, 4, v159
	v_lshl_add_u64 v[4:5], v[0:1], 0, v[176:177]
	global_load_dwordx4 v[42:45], v[4:5], off
	global_load_dwordx4 v[46:49], v[4:5], off offset:32
	global_load_dwordx4 v[50:53], v[4:5], off offset:64
	global_load_dwordx4 v[32:35], v[4:5], off offset:96
	global_load_dwordx4 v[28:31], v[4:5], off offset:128
	global_load_dwordx4 v[24:27], v[4:5], off offset:160
	global_load_dwordx4 v[20:23], v[4:5], off offset:192
	global_load_dwordx4 v[16:19], v[4:5], off offset:224
	global_load_dwordx4 v[8:11], v[4:5], off offset:256
	global_load_dwordx4 v[12:15], v[4:5], off offset:288
	global_load_dwordx4 v[0:3], v[4:5], off offset:320
	s_nop 0
	global_load_dwordx4 v[4:7], v[4:5], off offset:352
	v_and_b32_e32 v66, 63, v41
	s_add_i32 s6, 0, 0x14800
	v_lshlrev_b32_e32 v67, 4, v66
	v_add_u32_e32 v37, s6, v37
	v_add_u32_e32 v171, v37, v67
	s_mov_b64 s[6:7], 0x40040
	v_ashrrev_i32_e32 v148, 4, v41
	s_cmp_lg_u32 0, -1
	s_cselect_b32 s16, 0, 0
	v_ashrrev_i32_e32 v149, 31, v148
	v_lshl_add_u64 v[156:157], v[148:149], 0, 32
	s_mov_b32 s46, s45
	s_mov_b32 s47, s45
	s_mov_b32 s48, s45
	s_mov_b32 s49, s45
	s_mov_b32 s50, s45
	s_mov_b32 s51, s45
	s_mov_b32 s52, s45
	s_mov_b32 s53, s45
	s_mov_b32 s54, s45
	s_mov_b32 s55, s45
	s_mov_b32 s56, s45
	s_mov_b32 s57, s45
	s_mov_b32 s58, s45
	s_mov_b32 s59, s45
	s_mov_b32 s13, 2
	v_lshl_add_u32 v173, v168, 2, v169
	v_mov_b32_e32 v188, 0
	s_waitcnt vmcnt(0)
	v_and_b32_e32 v68, 0xffff0000, v42
	v_and_b32_e32 v70, 0xffff0000, v43
	v_lshlrev_b32_e32 v69, 16, v42
	v_mul_f32_e32 v38, v68, v68
	v_lshlrev_b32_e32 v71, 16, v43
	v_mul_f32_e32 v39, v70, v70
	v_fmac_f32_e32 v38, v69, v69
	v_fmac_f32_e32 v39, v71, v71
	v_and_b32_e32 v72, 0xffff0000, v44
	v_add_f32_e32 v38, v38, v39
	v_lshlrev_b32_e32 v73, 16, v44
	v_mul_f32_e32 v39, v72, v72
	v_fmac_f32_e32 v39, v73, v73
	v_and_b32_e32 v76, 0xffff0000, v45
	v_add_f32_e32 v38, v39, v38
	v_lshlrev_b32_e32 v77, 16, v45
	v_mul_f32_e32 v39, v76, v76
	v_fmac_f32_e32 v39, v77, v77
	v_and_b32_e32 v74, 0xffff0000, v46
	v_add_f32_e32 v38, v39, v38
	v_lshlrev_b32_e32 v75, 16, v46
	v_mul_f32_e32 v39, v74, v74
	v_fmac_f32_e32 v39, v75, v75
	v_and_b32_e32 v78, 0xffff0000, v47
	v_add_f32_e32 v38, v39, v38
	v_lshlrev_b32_e32 v79, 16, v47
	v_mul_f32_e32 v39, v78, v78
	v_fmac_f32_e32 v39, v79, v79
	v_and_b32_e32 v80, 0xffff0000, v48
	v_add_f32_e32 v38, v39, v38
	v_lshlrev_b32_e32 v82, 16, v48
	v_mul_f32_e32 v39, v80, v80
	v_fmac_f32_e32 v39, v82, v82
	v_and_b32_e32 v85, 0xffff0000, v49
	v_add_f32_e32 v38, v39, v38
	v_lshlrev_b32_e32 v86, 16, v49
	v_mul_f32_e32 v39, v85, v85
	v_fmac_f32_e32 v39, v86, v86
	v_and_b32_e32 v83, 0xffff0000, v50
	v_add_f32_e32 v38, v39, v38
	v_lshlrev_b32_e32 v84, 16, v50
	v_mul_f32_e32 v39, v83, v83
	v_fmac_f32_e32 v39, v84, v84
	v_and_b32_e32 v87, 0xffff0000, v51
	v_add_f32_e32 v38, v39, v38
	v_lshlrev_b32_e32 v88, 16, v51
	v_mul_f32_e32 v39, v87, v87
	v_fmac_f32_e32 v39, v88, v88
	v_and_b32_e32 v93, 0xffff0000, v52
	v_add_f32_e32 v38, v39, v38
	v_lshlrev_b32_e32 v95, 16, v52
	v_mul_f32_e32 v39, v93, v93
	v_fmac_f32_e32 v39, v95, v95
	v_and_b32_e32 v104, 0xffff0000, v53
	v_add_f32_e32 v38, v39, v38
	v_lshlrev_b32_e32 v105, 16, v53
	v_mul_f32_e32 v39, v104, v104
	v_and_b32_e32 v91, 0xffff0000, v32
	v_fmac_f32_e32 v39, v105, v105
	v_lshlrev_b32_e32 v108, 16, v32
	v_mul_f32_e32 v32, v91, v91
	v_and_b32_e32 v89, 0xffff0000, v33
	v_add_f32_e32 v38, v39, v38
	v_fmac_f32_e32 v32, v108, v108
	v_lshlrev_b32_e32 v94, 16, v33
	v_mul_f32_e32 v33, v89, v89
	v_add_f32_e32 v32, v32, v38
	v_fmac_f32_e32 v33, v94, v94
	v_and_b32_e32 v110, 0xffff0000, v34
	v_add_f32_e32 v32, v33, v32
	v_lshlrev_b32_e32 v112, 16, v34
	v_mul_f32_e32 v33, v110, v110
	v_fmac_f32_e32 v33, v112, v112
	v_and_b32_e32 v109, 0xffff0000, v35
	v_add_f32_e32 v32, v33, v32
	v_lshlrev_b32_e32 v111, 16, v35
	v_mul_f32_e32 v33, v109, v109
	v_and_b32_e32 v114, 0xffff0000, v28
	v_fmac_f32_e32 v33, v111, v111
	v_lshlrev_b32_e32 v113, 16, v28
	v_mul_f32_e32 v28, v114, v114
	v_and_b32_e32 v130, 0xffff0000, v29
	v_add_f32_e32 v32, v33, v32
	v_fmac_f32_e32 v28, v113, v113
	v_lshlrev_b32_e32 v115, 16, v29
	v_mul_f32_e32 v29, v130, v130
	v_add_f32_e32 v28, v28, v32
	v_fmac_f32_e32 v29, v115, v115
	v_and_b32_e32 v132, 0xffff0000, v30
	v_add_f32_e32 v28, v29, v28
	v_lshlrev_b32_e32 v131, 16, v30
	v_mul_f32_e32 v29, v132, v132
	v_fmac_f32_e32 v29, v131, v131
	v_and_b32_e32 v134, 0xffff0000, v31
	v_add_f32_e32 v28, v29, v28
	v_lshlrev_b32_e32 v133, 16, v31
	v_mul_f32_e32 v29, v134, v134
	v_and_b32_e32 v126, 0xffff0000, v24
	v_fmac_f32_e32 v29, v133, v133
	v_lshlrev_b32_e32 v128, 16, v24
	v_mul_f32_e32 v24, v126, v126
	v_and_b32_e32 v116, 0xffff0000, v25
	v_add_f32_e32 v28, v29, v28
	v_fmac_f32_e32 v24, v128, v128
	v_lshlrev_b32_e32 v118, 16, v25
	v_mul_f32_e32 v25, v116, v116
	v_add_f32_e32 v24, v24, v28
	v_fmac_f32_e32 v25, v118, v118
	v_and_b32_e32 v127, 0xffff0000, v26
	v_add_f32_e32 v24, v25, v24
	v_lshlrev_b32_e32 v129, 16, v26
	v_mul_f32_e32 v25, v127, v127
	v_fmac_f32_e32 v25, v129, v129
	v_and_b32_e32 v117, 0xffff0000, v27
	v_add_f32_e32 v24, v25, v24
	v_lshlrev_b32_e32 v119, 16, v27
	v_mul_f32_e32 v25, v117, v117
	v_and_b32_e32 v122, 0xffff0000, v20
	v_fmac_f32_e32 v25, v119, v119
	v_lshlrev_b32_e32 v124, 16, v20
	v_mul_f32_e32 v20, v122, v122
	v_and_b32_e32 v90, 0xffff0000, v21
	v_add_f32_e32 v24, v25, v24
	v_fmac_f32_e32 v20, v124, v124
	v_lshlrev_b32_e32 v120, 16, v21
	v_mul_f32_e32 v21, v90, v90
	v_add_f32_e32 v20, v20, v24
	v_fmac_f32_e32 v21, v120, v120
	v_and_b32_e32 v123, 0xffff0000, v22
	v_add_f32_e32 v20, v21, v20
	v_lshlrev_b32_e32 v125, 16, v22
	v_mul_f32_e32 v21, v123, v123
	v_fmac_f32_e32 v21, v125, v125
	v_and_b32_e32 v92, 0xffff0000, v23
	v_add_f32_e32 v20, v21, v20
	v_lshlrev_b32_e32 v121, 16, v23
	v_mul_f32_e32 v21, v92, v92
	v_fmac_f32_e32 v21, v121, v121
	v_add_f32_e32 v21, v21, v20
	v_and_b32_e32 v20, 0xffff0000, v16
	v_lshlrev_b32_e32 v22, 16, v16
	v_mul_f32_e32 v16, v20, v20
	v_fmac_f32_e32 v16, v22, v22
	v_add_f32_e32 v23, v16, v21
	v_and_b32_e32 v16, 0xffff0000, v17
	v_lshlrev_b32_e32 v21, 16, v17
	v_mul_f32_e32 v17, v16, v16
	v_fmac_f32_e32 v17, v21, v21
	v_lshlrev_b32_e32 v81, 16, v18
	v_and_b32_e32 v18, 0xffff0000, v18
	v_add_f32_e32 v17, v17, v23
	v_mul_f32_e32 v23, v18, v18
	v_fmac_f32_e32 v23, v81, v81
	v_add_f32_e32 v24, v23, v17
	v_and_b32_e32 v17, 0xffff0000, v19
	v_lshlrev_b32_e32 v23, 16, v19
	v_mul_f32_e32 v19, v17, v17
	v_fmac_f32_e32 v19, v23, v23
	v_add_f32_e32 v19, v19, v24
	v_and_b32_e32 v24, 32, v41
	global_load_dwordx4 v[96:99], v24, s[0:1] offset:16
	global_load_dwordx4 v[100:103], v24, s[0:1]
	global_load_dwordx4 v[240:243], v24, s[0:1] offset:80
	global_load_dwordx4 v[244:247], v24, s[0:1] offset:64
	global_load_dwordx4 v[248:251], v24, s[0:1] offset:144
	global_load_dwordx4 v[220:223], v24, s[0:1] offset:128
	global_load_dwordx4 v[232:235], v24, s[0:1] offset:208
	global_load_dwordx4 v[236:239], v24, s[0:1] offset:192
	v_and_b32_e32 v63, 0xffff0000, v12
	v_and_b32_e32 v62, 0xffff0000, v8
	v_mov_b32_e32 v25, v177
	v_lshlrev_b32_e32 v60, 16, v9
	v_and_b32_e32 v59, 0xffff0000, v13
	v_and_b32_e32 v58, 0xffff0000, v9
	v_lshlrev_b32_e32 v65, 16, v12
	v_lshlrev_b32_e32 v64, 16, v8
	v_pk_mul_f32 v[8:9], v[62:63], v[62:63]
	v_lshl_add_u64 v[26:27], s[40:41], 0, v[24:25]
	v_lshlrev_b32_e32 v25, 7, v36
	v_lshlrev_b32_e32 v39, 16, v15
	v_and_b32_e32 v37, 0xffff0000, v15
	v_lshlrev_b32_e32 v51, 16, v14
	v_and_b32_e32 v49, 0xffff0000, v14
	v_and_b32_e32 v48, 0xffff0000, v10
	v_lshlrev_b32_e32 v61, 16, v13
	v_pk_mul_f32 v[14:15], v[58:59], v[58:59]
	v_pk_fma_f32 v[8:9], v[64:65], v[64:65], v[8:9]
	v_and_b32_e32 v28, 0x3ff80, v25
	v_mov_b32_e32 v29, v177
	v_lshlrev_b32_e32 v38, 16, v11
	v_and_b32_e32 v36, 0xffff0000, v11
	v_lshlrev_b32_e32 v50, 16, v10
	v_pk_mul_f32 v[10:11], v[48:49], v[48:49]
	v_pk_fma_f32 v[14:15], v[60:61], v[60:61], v[14:15]
	v_add_f32_e32 v8, v8, v19
	v_lshl_add_u64 v[28:29], v[26:27], 0, v[28:29]
	v_pk_mul_f32 v[26:27], v[36:37], v[36:37]
	v_pk_fma_f32 v[10:11], v[50:51], v[50:51], v[10:11]
	v_add_f32_e32 v8, v14, v8
	v_pk_fma_f32 v[26:27], v[38:39], v[38:39], v[26:27]
	v_add_f32_e32 v8, v10, v8
	v_add_f32_e32 v8, v26, v8
	v_add_f32_e32 v8, v9, v8
	v_add_f32_e32 v8, v15, v8
	v_add_f32_e32 v8, v11, v8
	v_and_b32_e32 v26, 0xffff0000, v3
	v_and_b32_e32 v32, 0xffff0000, v2
	v_add_f32_e32 v10, v27, v8
	v_lshlrev_b32_e32 v31, 16, v7
	v_lshlrev_b32_e32 v30, 16, v3
	v_and_b32_e32 v27, 0xffff0000, v7
	v_lshlrev_b32_e32 v35, 16, v6
	v_lshlrev_b32_e32 v34, 16, v2
	v_and_b32_e32 v33, 0xffff0000, v6
	v_mov_b32_e32 v6, v26
	v_mov_b32_e32 v7, v32
	v_mov_b32_e32 v2, v30
	v_mov_b32_e32 v3, v34
	v_pk_mul_f32 v[6:7], v[6:7], v[6:7]
	v_mov_b32_e32 v8, v27
	v_mov_b32_e32 v9, v33
	v_pk_fma_f32 v[2:3], v[2:3], v[2:3], v[6:7]
	v_mov_b32_e32 v6, v31
	v_mov_b32_e32 v7, v35
	v_pk_mul_f32 v[8:9], v[8:9], v[8:9]
	v_and_b32_e32 v43, 0xffff0000, v5
	v_lshlrev_b32_e32 v56, 16, v0
	v_and_b32_e32 v53, 0xffff0000, v4
	v_pk_fma_f32 v[6:7], v[6:7], v[6:7], v[8:9]
	v_lshlrev_b32_e32 v47, 16, v5
	v_lshlrev_b32_e32 v46, 16, v1
	v_lshlrev_b32_e32 v57, 16, v4
	v_and_b32_e32 v52, 0xffff0000, v0
	v_mul_f32_e32 v9, v56, v56
	v_mov_b32_e32 v4, v43
	v_mov_b32_e32 v5, v53
	v_and_b32_e32 v42, 0xffff0000, v1
	v_mul_f32_e32 v8, v46, v46
	v_fmac_f32_e32 v9, v52, v52
	v_mov_b32_e32 v0, v47
	v_mov_b32_e32 v1, v57
	v_pk_mul_f32 v[4:5], v[4:5], v[4:5]
	v_fmac_f32_e32 v8, v42, v42
	v_pk_fma_f32 v[0:1], v[0:1], v[0:1], v[4:5]
	v_add_f32_e32 v4, v9, v10
	v_add_f32_e32 v4, v8, v4
	v_add_f32_e32 v3, v3, v4
	v_add_f32_e32 v2, v2, v3
	v_add_f32_e32 v1, v1, v2
	v_add_f32_e32 v0, v0, v1
	v_add_f32_e32 v0, v7, v0
	v_add_f32_e32 v0, v6, v0
	v_mov_b32_e32 v1, v0
	s_nop 1
	v_permlane32_swap_b32_e32 v0, v1
	v_add_f32_e32 v0, v0, v1
	v_fmamk_f32 v0, v0, 0x3baaaaab, v216
	v_cmp_gt_f32_e32 vcc, s85, v0
	v_mul_f32_e32 v1, 0x4b800000, v0
	v_lshl_add_u64 v[54:55], v[28:29], 0, s[30:31]
	v_cndmask_b32_e32 v0, v0, v1, vcc
	v_rsq_f32_e32 v0, v0
	v_lshl_add_u64 v[44:45], v[28:29], 0, s[6:7]
	v_mul_f32_e32 v1, 0x45800000, v0
	v_cndmask_b32_e32 v0, v0, v1, vcc
	v_mul_f32_e32 v40, 0x3dd53b94, v0
	v_mul_f32_e32 v0, v40, v69
	v_mul_f32_e32 v1, v40, v73
	v_mul_f32_e32 v2, v40, v68
	v_mul_f32_e32 v3, v40, v72
	v_mul_f32_e32 v4, v40, v71
	v_mul_f32_e32 v5, v40, v77
	v_mul_f32_e32 v6, v40, v70
	v_mul_f32_e32 v7, v40, v76
	s_waitcnt vmcnt(0)
	v_mul_f32_e32 v0, v100, v0
	v_mul_f32_e32 v1, v96, v1
	v_mul_f32_e32 v2, v101, v2
	v_mul_f32_e32 v3, v97, v3
	v_mul_f32_e32 v4, v102, v4
	v_mul_f32_e32 v5, v98, v5
	v_mul_f32_e32 v6, v103, v6
	v_mul_f32_e32 v7, v99, v7
	v_cvt_pk_bf16_f32 v96, v0, v2
	v_cvt_pk_bf16_f32 v97, v4, v6
	v_cvt_pk_bf16_f32 v98, v1, v3
	v_cvt_pk_bf16_f32 v99, v5, v7
	s_nop 1
	v_mov_b32_e32 v0, v240
	v_mov_b32_e32 v1, v241
	v_mov_b32_e32 v2, v242
	v_mov_b32_e32 v3, v243
	v_mov_b32_e32 v4, v244
	v_mov_b32_e32 v5, v245
	v_mov_b32_e32 v6, v246
	v_mov_b32_e32 v7, v247
	global_load_dwordx4 v[240:243], v24, s[0:1] offset:272
	global_load_dwordx4 v[244:247], v24, s[0:1] offset:256
	v_mul_f32_e32 v8, v40, v75
	v_add_co_u32_e32 v76, vcc, s88, v28
	v_mul_f32_e32 v4, v4, v8
	v_mul_f32_e32 v8, v40, v82
	v_mul_f32_e32 v0, v0, v8
	v_mul_f32_e32 v8, v40, v74
	v_mul_f32_e32 v5, v5, v8
	v_mul_f32_e32 v8, v40, v80
	v_mul_f32_e32 v1, v1, v8
	v_mul_f32_e32 v8, v40, v79
	v_mul_f32_e32 v6, v6, v8
	v_mul_f32_e32 v8, v40, v86
	v_mul_f32_e32 v2, v2, v8
	v_mul_f32_e32 v8, v40, v78
	v_mul_f32_e32 v7, v7, v8
	v_mul_f32_e32 v8, v40, v85
	v_mul_f32_e32 v3, v3, v8
	v_cvt_pk_bf16_f32 v100, v4, v5
	v_cvt_pk_bf16_f32 v101, v6, v7
	v_cvt_pk_bf16_f32 v102, v0, v1
	v_cvt_pk_bf16_f32 v103, v2, v3
	s_nop 1
	v_mov_b32_e32 v0, v248
	v_mov_b32_e32 v1, v249
	v_mov_b32_e32 v2, v250
	v_mov_b32_e32 v3, v251
	v_mov_b32_e32 v4, v220
	v_mov_b32_e32 v5, v221
	v_mov_b32_e32 v6, v222
	v_mov_b32_e32 v7, v223
	global_load_dwordx4 v[248:251], v24, s[0:1] offset:336
	global_load_dwordx4 v[220:223], v24, s[0:1] offset:320
	v_mul_f32_e32 v8, v40, v84
	v_addc_co_u32_e32 v77, vcc, 0, v29, vcc
	v_mul_f32_e32 v4, v8, v4
	v_mul_f32_e32 v8, v40, v95
	v_mul_f32_e32 v0, v8, v0
	v_mul_f32_e32 v8, v40, v83
	v_mul_f32_e32 v5, v8, v5
	v_mul_f32_e32 v8, v40, v93
	v_mul_f32_e32 v1, v8, v1
	v_mul_f32_e32 v8, v40, v88
	v_mul_f32_e32 v6, v8, v6
	v_mul_f32_e32 v8, v40, v105
	v_mul_f32_e32 v2, v8, v2
	v_mul_f32_e32 v8, v40, v87
	v_mul_f32_e32 v7, v8, v7
	v_mul_f32_e32 v8, v40, v104
	v_mul_f32_e32 v3, v8, v3
	v_cvt_pk_bf16_f32 v104, v4, v5
	v_cvt_pk_bf16_f32 v105, v6, v7
	v_cvt_pk_bf16_f32 v106, v0, v1
	v_cvt_pk_bf16_f32 v107, v2, v3
	s_nop 1
	v_mov_b32_e32 v0, v232
	v_mov_b32_e32 v1, v233
	v_mov_b32_e32 v2, v234
	v_mov_b32_e32 v3, v235
	v_mov_b32_e32 v4, v236
	v_mov_b32_e32 v5, v237
	v_mov_b32_e32 v6, v238
	v_mov_b32_e32 v7, v239
	global_load_dwordx4 v[232:235], v24, s[0:1] offset:400
	global_load_dwordx4 v[236:239], v24, s[0:1] offset:384
	v_mul_f32_e32 v8, v40, v108
	v_mul_f32_e32 v4, v8, v4
	v_mul_f32_e32 v8, v40, v112
	v_mul_f32_e32 v0, v8, v0
	v_mul_f32_e32 v8, v40, v91
	v_mul_f32_e32 v5, v8, v5
	v_mul_f32_e32 v8, v40, v110
	v_mul_f32_e32 v1, v8, v1
	v_mul_f32_e32 v8, v40, v94
	v_mul_f32_e32 v6, v8, v6
	v_mul_f32_e32 v8, v40, v111
	v_mul_f32_e32 v2, v8, v2
	v_mul_f32_e32 v8, v40, v89
	v_mul_f32_e32 v7, v8, v7
	v_mul_f32_e32 v8, v40, v109
	v_mul_f32_e32 v3, v8, v3
	v_cvt_pk_bf16_f32 v108, v4, v5
	v_cvt_pk_bf16_f32 v109, v6, v7
	v_cvt_pk_bf16_f32 v110, v0, v1
	v_cvt_pk_bf16_f32 v111, v2, v3
	s_waitcnt vmcnt(4)
	s_nop 1
	v_mov_b32_e32 v0, v240
	v_mov_b32_e32 v1, v241
	v_mov_b32_e32 v2, v242
	v_mov_b32_e32 v3, v243
	v_mov_b32_e32 v4, v244
	v_mov_b32_e32 v5, v245
	v_mov_b32_e32 v6, v246
	v_mov_b32_e32 v7, v247
	global_load_dwordx4 v[240:243], v24, s[0:1] offset:464
	global_load_dwordx4 v[244:247], v24, s[0:1] offset:448
	v_mul_f32_e32 v8, v40, v113
	v_mul_f32_e32 v4, v8, v4
	v_mul_f32_e32 v8, v40, v131
	v_mul_f32_e32 v0, v8, v0
	v_mul_f32_e32 v8, v40, v114
	v_mul_f32_e32 v5, v8, v5
	v_mul_f32_e32 v8, v40, v132
	v_mul_f32_e32 v1, v8, v1
	v_mul_f32_e32 v8, v40, v115
	v_mul_f32_e32 v6, v8, v6
	v_mul_f32_e32 v8, v40, v133
	v_mul_f32_e32 v2, v8, v2
	v_mul_f32_e32 v8, v40, v130
	v_mul_f32_e32 v7, v8, v7
	v_mul_f32_e32 v8, v40, v134
	v_mul_f32_e32 v3, v8, v3
	v_cvt_pk_bf16_f32 v112, v4, v5
	v_cvt_pk_bf16_f32 v113, v6, v7
	v_cvt_pk_bf16_f32 v114, v0, v1
	v_cvt_pk_bf16_f32 v115, v2, v3
	s_waitcnt vmcnt(4)
	s_nop 1
	v_mov_b32_e32 v0, v248
	v_mov_b32_e32 v1, v249
	v_mov_b32_e32 v2, v250
	v_mov_b32_e32 v3, v251
	v_mov_b32_e32 v4, v220
	v_mov_b32_e32 v5, v221
	v_mov_b32_e32 v6, v222
	v_mov_b32_e32 v7, v223
	v_mul_f32_e32 v8, v40, v128
	v_mul_f32_e32 v4, v8, v4
	v_mul_f32_e32 v8, v40, v129
	v_mul_f32_e32 v0, v8, v0
	v_mul_f32_e32 v8, v40, v126
	v_mul_f32_e32 v5, v8, v5
	v_mul_f32_e32 v8, v40, v127
	v_mul_f32_e32 v1, v8, v1
	v_mul_f32_e32 v8, v40, v118
	v_mul_f32_e32 v6, v8, v6
	v_mul_f32_e32 v8, v40, v119
	v_mul_f32_e32 v2, v8, v2
	v_mul_f32_e32 v8, v40, v116
	v_mul_f32_e32 v7, v8, v7
	v_mul_f32_e32 v8, v40, v117
	v_mul_f32_e32 v3, v8, v3
	v_cvt_pk_bf16_f32 v116, v4, v5
	v_cvt_pk_bf16_f32 v117, v6, v7
	v_cvt_pk_bf16_f32 v118, v0, v1
	v_cvt_pk_bf16_f32 v119, v2, v3
	s_waitcnt vmcnt(2)
	s_nop 1
	v_mov_b32_e32 v0, v232
	v_mov_b32_e32 v1, v233
	v_mov_b32_e32 v2, v234
	v_mov_b32_e32 v3, v235
	v_mov_b32_e32 v4, v236
	v_mov_b32_e32 v5, v237
	v_mov_b32_e32 v6, v238
	v_mov_b32_e32 v7, v239
	v_mul_f32_e32 v8, v40, v124
	v_mul_f32_e32 v4, v8, v4
	v_mul_f32_e32 v8, v40, v125
	v_mul_f32_e32 v8, v8, v0
	v_mul_f32_e32 v0, v40, v122
	v_mul_f32_e32 v0, v0, v5
	v_mul_f32_e32 v5, v40, v123
	v_mul_f32_e32 v5, v5, v1
	v_mul_f32_e32 v1, v40, v120
	v_mul_f32_e32 v1, v1, v6
	v_mul_f32_e32 v6, v40, v121
	v_mul_f32_e32 v6, v6, v2
	v_mul_f32_e32 v2, v40, v90
	v_mul_f32_e32 v2, v2, v7
	v_mul_f32_e32 v7, v40, v92
	v_mul_f32_e32 v3, v7, v3
	v_cvt_pk_bf16_f32 v0, v4, v0
	v_cvt_pk_bf16_f32 v1, v1, v2
	v_cvt_pk_bf16_f32 v2, v8, v5
	v_cvt_pk_bf16_f32 v3, v6, v3
	ds_write_b128 v171, v[0:3]
	s_waitcnt vmcnt(0)
	s_nop 1
	v_mov_b32_e32 v0, v240
	v_mov_b32_e32 v1, v241
	v_mov_b32_e32 v2, v242
	v_mov_b32_e32 v3, v243
	v_mov_b32_e32 v4, v244
	v_mov_b32_e32 v5, v245
	v_mov_b32_e32 v6, v246
	v_mov_b32_e32 v7, v247
	v_mul_f32_e32 v8, v40, v22
	v_mul_f32_e32 v4, v8, v4
	v_mul_f32_e32 v8, v40, v81
	v_mul_f32_e32 v8, v8, v0
	v_mul_f32_e32 v0, v40, v20
	v_mul_f32_e32 v0, v0, v5
	v_mul_f32_e32 v5, v40, v18
	v_mul_f32_e32 v5, v5, v1
	v_mul_f32_e32 v1, v40, v21
	v_mul_f32_e32 v1, v1, v6
	v_mul_f32_e32 v6, v40, v23
	v_mul_f32_e32 v6, v6, v2
	v_mul_f32_e32 v2, v40, v16
	v_mul_f32_e32 v2, v2, v7
	v_mul_f32_e32 v7, v40, v17
	v_mul_f32_e32 v3, v7, v3
	v_cvt_pk_bf16_f32 v0, v4, v0
	v_cvt_pk_bf16_f32 v1, v1, v2
	v_cvt_pk_bf16_f32 v2, v8, v5
	v_cvt_pk_bf16_f32 v3, v6, v3
	ds_write_b128 v171, v[0:3] offset:1024
	global_load_dwordx4 v[4:7], v24, s[0:1] offset:528
	global_load_dwordx4 v[16:19], v24, s[0:1] offset:512
	global_load_dwordx4 v[8:11], v24, s[0:1] offset:592
	global_load_dwordx4 v[20:23], v24, s[0:1] offset:576
	global_load_dwordx4 v[0:3], v[28:29], off offset:16
	global_load_dwordx4 v[12:15], v[28:29], off
	global_load_dwordx4 v[68:71], v[76:77], off
	global_load_dwordx4 v[72:75], v[54:55], off offset:16
	v_pk_mul_f32 v[54:55], v[40:41], v[64:65] op_sel_hi:[0,1]
	s_waitcnt vmcnt(6)
	v_mov_b32_e32 v64, v16
	s_waitcnt vmcnt(4)
	v_mov_b32_e32 v65, v20
	v_pk_mul_f32 v[54:55], v[54:55], v[64:65]
	s_waitcnt vmcnt(2)
	v_mov_b32_e32 v64, v12
	s_waitcnt vmcnt(1)
	v_mov_b32_e32 v65, v68
	v_pk_mul_f32 v[64:65], v[54:55], v[64:65]
	v_mov_b32_e32 v20, v17
	v_sub_f32_e32 v16, v64, v65
	v_mov_b32_e32 v64, v68
	v_mov_b32_e32 v65, v12
	v_pk_mul_f32 v[64:65], v[54:55], v[64:65]
	v_cndmask_b32_e64 v25, v54, v16, s[2:3]
	v_add_f32_e32 v12, v65, v64
	v_cndmask_b32_e64 v64, v55, v12, s[2:3]
	v_pk_mul_f32 v[54:55], v[40:41], v[62:63] op_sel_hi:[0,1]
	v_pk_mul_f32 v[16:17], v[54:55], v[20:21]
	v_mov_b32_e32 v68, v13
	v_pk_mul_f32 v[20:21], v[16:17], v[68:69]
	v_or_b32_e32 v65, 32, v176
	v_sub_f32_e32 v12, v20, v21
	v_cndmask_b32_e64 v20, v16, v12, s[2:3]
	v_mov_b32_e32 v12, v69
	v_pk_mul_f32 v[12:13], v[16:17], v[12:13]
	v_mov_b32_e32 v16, v18
	v_add_f32_e32 v12, v13, v12
	v_cndmask_b32_e64 v21, v17, v12, s[2:3]
	v_pk_mul_f32 v[12:13], v[40:41], v[60:61] op_sel_hi:[0,1]
	v_mov_b32_e32 v17, v22
	v_pk_mul_f32 v[12:13], v[12:13], v[16:17]
	v_mov_b32_e32 v16, v14
	v_mov_b32_e32 v17, v70
	v_pk_mul_f32 v[16:17], v[12:13], v[16:17]
	v_mov_b32_e32 v22, v19
	v_sub_f32_e32 v16, v16, v17
	v_cndmask_b32_e64 v18, v12, v16, s[2:3]
	v_mov_b32_e32 v16, v70
	v_mov_b32_e32 v17, v14
	v_pk_mul_f32 v[16:17], v[12:13], v[16:17]
	v_mov_b32_e32 v70, v15
	v_add_f32_e32 v12, v17, v16
	v_cndmask_b32_e64 v54, v13, v12, s[2:3]
	v_pk_mul_f32 v[12:13], v[40:41], v[58:59] op_sel_hi:[0,1]
	v_pk_mul_f32 v[12:13], v[12:13], v[22:23]
	v_mul_u32_u24_e32 v59, 0x180, v168
	v_pk_mul_f32 v[16:17], v[12:13], v[70:71]
	s_nop 0
	v_sub_f32_e32 v14, v16, v17
	v_cndmask_b32_e64 v16, v12, v14, s[2:3]
	v_mov_b32_e32 v14, v71
	v_pk_mul_f32 v[14:15], v[12:13], v[14:15]
	s_nop 0
	v_add_f32_e32 v12, v15, v14
	v_cndmask_b32_e64 v17, v13, v12, s[2:3]
	v_pk_mul_f32 v[12:13], v[40:41], v[50:51] op_sel_hi:[0,1]
	v_mov_b32_e32 v14, v4
	v_mov_b32_e32 v15, v8
	v_pk_mul_f32 v[12:13], v[12:13], v[14:15]
	v_mov_b32_e32 v14, v0
	s_waitcnt vmcnt(0)
	v_mov_b32_e32 v15, v72
	v_pk_mul_f32 v[14:15], v[12:13], v[14:15]
	v_mov_b32_e32 v8, v5
	v_sub_f32_e32 v4, v14, v15
	v_mov_b32_e32 v14, v72
	v_mov_b32_e32 v15, v0
	v_pk_mul_f32 v[14:15], v[12:13], v[14:15]
	v_cndmask_b32_e64 v19, v12, v4, s[2:3]
	v_add_f32_e32 v0, v15, v14
	v_cndmask_b32_e64 v14, v13, v0, s[2:3]
	v_pk_mul_f32 v[12:13], v[40:41], v[48:49] op_sel_hi:[0,1]
	v_pk_mul_f32 v[4:5], v[12:13], v[8:9]
	v_mov_b32_e32 v72, v1
	v_pk_mul_f32 v[8:9], v[4:5], v[72:73]
	s_nop 0
	v_sub_f32_e32 v0, v8, v9
	v_cndmask_b32_e64 v8, v4, v0, s[2:3]
	v_mov_b32_e32 v0, v73
	v_pk_mul_f32 v[0:1], v[4:5], v[0:1]
	v_mov_b32_e32 v4, v6
	v_add_f32_e32 v0, v1, v0
	v_cndmask_b32_e64 v9, v5, v0, s[2:3]
	v_pk_mul_f32 v[0:1], v[40:41], v[38:39] op_sel_hi:[0,1]
	v_mov_b32_e32 v5, v10
	v_pk_mul_f32 v[0:1], v[0:1], v[4:5]
	v_mov_b32_e32 v4, v2
	v_mov_b32_e32 v5, v74
	v_pk_mul_f32 v[4:5], v[0:1], v[4:5]
	v_mov_b32_e32 v10, v7
	v_sub_f32_e32 v4, v4, v5
	v_cndmask_b32_e64 v6, v0, v4, s[2:3]
	v_mov_b32_e32 v4, v74
	v_mov_b32_e32 v5, v2
	v_pk_mul_f32 v[4:5], v[0:1], v[4:5]
	v_mov_b32_e32 v74, v3
	v_add_f32_e32 v0, v5, v4
	v_cndmask_b32_e64 v12, v1, v0, s[2:3]
	v_pk_mul_f32 v[0:1], v[40:41], v[36:37] op_sel_hi:[0,1]
	v_pk_mul_f32 v[0:1], v[0:1], v[10:11]
	s_nop 0
	v_pk_mul_f32 v[4:5], v[0:1], v[74:75]
	s_nop 0
	v_sub_f32_e32 v2, v4, v5
	v_cndmask_b32_e64 v4, v0, v2, s[2:3]
	v_mov_b32_e32 v2, v75
	v_pk_mul_f32 v[2:3], v[0:1], v[2:3]
	s_nop 0
	v_add_f32_e32 v0, v3, v2
	v_cndmask_b32_e64 v5, v1, v0, s[2:3]
	v_cvt_pk_bf16_f32 v0, v25, v20
	v_cvt_pk_bf16_f32 v1, v18, v16
	v_cvt_pk_bf16_f32 v2, v19, v8
	v_cvt_pk_bf16_f32 v3, v6, v4
	ds_write_b128 v171, v[0:3] offset:2048
	v_cvt_pk_bf16_f32 v0, v64, v21
	v_cvt_pk_bf16_f32 v1, v54, v17
	v_cvt_pk_bf16_f32 v2, v14, v9
	v_cvt_pk_bf16_f32 v3, v12, v5
	ds_write_b128 v171, v[0:3] offset:3072
	global_load_dwordx4 v[0:3], v24, s[0:1] offset:656
	global_load_dwordx4 v[4:7], v24, s[0:1] offset:640
	global_load_dwordx4 v[8:11], v24, s[0:1] offset:720
	global_load_dwordx4 v[12:15], v24, s[0:1] offset:704
	global_load_dwordx4 v[16:19], v[28:29], off offset:80
	global_load_dwordx4 v[20:23], v[28:29], off offset:64
	global_load_dwordx4 v[36:39], v[76:77], off offset:64
	global_load_dwordx4 v[48:51], v[44:45], off offset:16
	v_pk_mul_f32 v[24:25], v[40:41], v[56:57] op_sel_hi:[0,1]
	s_waitcnt vmcnt(6)
	v_mov_b32_e32 v28, v4
	s_waitcnt vmcnt(4)
	v_mov_b32_e32 v29, v12
	v_pk_mul_f32 v[24:25], v[24:25], v[28:29]
	s_waitcnt vmcnt(2)
	v_mov_b32_e32 v28, v20
	s_waitcnt vmcnt(1)
	v_mov_b32_e32 v29, v36
	v_pk_mul_f32 v[28:29], v[24:25], v[28:29]
	v_mov_b32_e32 v12, v5
	v_sub_f32_e32 v4, v28, v29
	v_mov_b32_e32 v28, v36
	v_mov_b32_e32 v29, v20
	v_pk_mul_f32 v[28:29], v[24:25], v[28:29]
	v_cndmask_b32_e64 v44, v24, v4, s[2:3]
	v_add_f32_e32 v4, v29, v28
	v_cndmask_b32_e64 v28, v25, v4, s[2:3]
	v_pk_mul_f32 v[24:25], v[40:41], v[52:53] op_sel_hi:[0,1]
	v_pk_mul_f32 v[4:5], v[24:25], v[12:13]
	v_mov_b32_e32 v36, v21
	v_pk_mul_f32 v[12:13], v[4:5], v[36:37]
	v_mov_b32_e32 v20, v37
	v_sub_f32_e32 v12, v12, v13
	v_cndmask_b32_e64 v24, v4, v12, s[2:3]
	v_pk_mul_f32 v[12:13], v[4:5], v[20:21]
	s_nop 0
	v_add_f32_e32 v4, v13, v12
	v_cndmask_b32_e64 v20, v5, v4, s[2:3]
	v_pk_mul_f32 v[4:5], v[40:41], v[46:47] op_sel_hi:[0,1]
	v_mov_b32_e32 v12, v6
	v_mov_b32_e32 v13, v14
	v_pk_mul_f32 v[4:5], v[4:5], v[12:13]
	v_mov_b32_e32 v12, v22
	v_mov_b32_e32 v13, v38
	v_pk_mul_f32 v[12:13], v[4:5], v[12:13]
	v_mov_b32_e32 v14, v7
	v_sub_f32_e32 v6, v12, v13
	v_mov_b32_e32 v12, v38
	v_mov_b32_e32 v13, v22
	v_pk_mul_f32 v[12:13], v[4:5], v[12:13]
	v_cndmask_b32_e64 v21, v4, v6, s[2:3]
	v_add_f32_e32 v4, v13, v12
	v_cndmask_b32_e64 v12, v5, v4, s[2:3]
	v_pk_mul_f32 v[4:5], v[40:41], v[42:43] op_sel_hi:[0,1]
	v_pk_mul_f32 v[4:5], v[4:5], v[14:15]
	v_mov_b32_e32 v38, v23
	v_pk_mul_f32 v[6:7], v[4:5], v[38:39]
	v_mov_b32_e32 v22, v39
	v_sub_f32_e32 v6, v6, v7
	v_cndmask_b32_e64 v13, v4, v6, s[2:3]
	v_pk_mul_f32 v[6:7], v[4:5], v[22:23]
	s_nop 0
	v_add_f32_e32 v4, v7, v6
	v_cndmask_b32_e64 v14, v5, v4, s[2:3]
	v_pk_mul_f32 v[4:5], v[40:41], v[34:35] op_sel_hi:[0,1]
	v_mov_b32_e32 v6, v0
	v_mov_b32_e32 v7, v8
	v_pk_mul_f32 v[4:5], v[4:5], v[6:7]
	v_mov_b32_e32 v6, v16
	s_waitcnt vmcnt(0)
	v_mov_b32_e32 v7, v48
	v_pk_mul_f32 v[6:7], v[4:5], v[6:7]
	v_mov_b32_e32 v8, v1
	v_sub_f32_e32 v0, v6, v7
	v_mov_b32_e32 v6, v48
	v_mov_b32_e32 v7, v16
	v_pk_mul_f32 v[6:7], v[4:5], v[6:7]
	v_cndmask_b32_e64 v15, v4, v0, s[2:3]
	v_add_f32_e32 v0, v7, v6
	v_cndmask_b32_e64 v6, v5, v0, s[2:3]
	v_pk_mul_f32 v[4:5], v[40:41], v[32:33] op_sel_hi:[0,1]
	v_pk_mul_f32 v[0:1], v[4:5], v[8:9]
	v_mov_b32_e32 v48, v17
	v_pk_mul_f32 v[4:5], v[0:1], v[48:49]
	v_mov_b32_e32 v16, v49
	v_sub_f32_e32 v4, v4, v5
	v_cndmask_b32_e64 v7, v0, v4, s[2:3]
	v_pk_mul_f32 v[4:5], v[0:1], v[16:17]
	v_mov_b32_e32 v49, v177
	v_add_f32_e32 v0, v5, v4
	v_cndmask_b32_e64 v8, v1, v0, s[2:3]
	v_pk_mul_f32 v[0:1], v[40:41], v[30:31] op_sel_hi:[0,1]
	v_mov_b32_e32 v4, v2
	v_mov_b32_e32 v5, v10
	v_pk_mul_f32 v[0:1], v[0:1], v[4:5]
	v_mov_b32_e32 v4, v18
	v_mov_b32_e32 v5, v50
	v_pk_mul_f32 v[4:5], v[0:1], v[4:5]
	v_mov_b32_e32 v10, v3
	v_sub_f32_e32 v2, v4, v5
	v_mov_b32_e32 v4, v50
	v_mov_b32_e32 v5, v18
	v_pk_mul_f32 v[4:5], v[0:1], v[4:5]
	v_cndmask_b32_e64 v9, v0, v2, s[2:3]
	v_add_f32_e32 v0, v5, v4
	v_cndmask_b32_e64 v4, v1, v0, s[2:3]
	v_pk_mul_f32 v[0:1], v[40:41], v[26:27] op_sel_hi:[0,1]
	v_pk_mul_f32 v[0:1], v[0:1], v[10:11]
	v_mov_b32_e32 v50, v19
	v_pk_mul_f32 v[2:3], v[0:1], v[50:51]
	v_mov_b32_e32 v18, v51
	v_sub_f32_e32 v2, v2, v3
	v_cndmask_b32_e64 v5, v0, v2, s[2:3]
	v_pk_mul_f32 v[2:3], v[0:1], v[18:19]
	v_lshlrev_b32_e32 v18, 4, v41
	v_add_f32_e32 v0, v3, v2
	v_cndmask_b32_e64 v10, v1, v0, s[2:3]
	v_cvt_pk_bf16_f32 v0, v44, v24
	v_cvt_pk_bf16_f32 v1, v21, v13
	v_cvt_pk_bf16_f32 v2, v15, v7
	v_cvt_pk_bf16_f32 v3, v9, v5
	ds_write_b128 v171, v[0:3] offset:4096
	v_cvt_pk_bf16_f32 v0, v28, v20
	v_cvt_pk_bf16_f32 v1, v12, v14
	v_cvt_pk_bf16_f32 v2, v6, v8
	v_cvt_pk_bf16_f32 v3, v4, v10
	ds_write_b128 v171, v[0:3] offset:5120
	v_and_b32_e32 v1, 0xfffff0, v148
	v_lshlrev_b32_e32 v3, 1, v148
	v_lshlrev_b32_e32 v0, 3, v41
	v_and_or_b32 v1, v3, 8, v1
	v_and_b32_e32 v2, 0x78, v0
	v_lshrrev_b32_e32 v3, 1, v148
	v_lshrrev_b32_e32 v1, 1, v1
	v_bfe_u32 v0, v0, 5, 2
	v_and_b32_e32 v4, 3, v148
	v_or_b32_e32 v1, v1, v0
	v_and_or_b32 v3, v3, 4, v4
	v_lshlrev_b32_e32 v1, 9, v1
	v_lshlrev_b32_e32 v3, 6, v3
	v_and_b32_e32 v4, 48, v18
	v_or3_b32 v19, v1, v3, v4
	v_add_u32_e32 v1, 32, v148
	v_and_b32_e32 v5, 0xfffff0, v1
	v_lshlrev_b32_e32 v1, 1, v1
	v_and_or_b32 v1, v1, 8, v5
	v_lshrrev_b32_e32 v1, 1, v1
	v_or_b32_e32 v0, v1, v0
	v_lshlrev_b32_e32 v0, 9, v0
	s_mov_b32 s2, 0x2aaaaaab
	v_or3_b32 v20, v0, v3, v4
	v_mul_hi_i32 v0, v41, s2
	v_lshrrev_b32_e32 v1, 31, v0
	v_ashrrev_i32_e32 v0, 2, v0
	v_add_u32_e32 v150, v0, v1
	v_add_u32_e32 v1, 0x200, v41
	v_mul_hi_i32 v3, v1, s2
	v_lshrrev_b32_e32 v4, 31, v3
	v_ashrrev_i32_e32 v3, 2, v3
	v_add_u32_e32 v152, v3, v4
	v_mul_lo_u32 v3, v152, 24
	v_sub_u32_e32 v1, v1, v3
	v_add_u32_e32 v3, 0x400, v41
	v_mul_hi_i32 v4, v3, s2
	v_lshrrev_b32_e32 v5, 31, v4
	v_ashrrev_i32_e32 v4, 2, v4
	v_mul_lo_u32 v0, v150, 24
	v_add_u32_e32 v154, v4, v5
	s_add_u32 s2, s94, s44
	v_sub_u32_e32 v0, v41, v0
	v_mul_lo_u32 v4, v154, 24
	s_addc_u32 s3, s95, 0
	s_lshl_b32 s5, s5, 8
	v_lshlrev_b32_e32 v8, 3, v0
	v_sub_u32_e32 v3, v3, v4
	v_mul_lo_u32 v4, v150, s89
	v_bitop3_b32 v0, v150, v0, 7 bitop3:0x6c
	s_add_u32 s6, s38, s5
	v_lshlrev_b32_e32 v12, 3, v1
	v_lshl_add_u32 v21, v0, 4, v4
	v_mul_lo_u32 v0, v152, s89
	v_bitop3_b32 v1, v152, v1, 7 bitop3:0x6c
	s_addc_u32 s7, s39, 0
	s_ashr_i32 s5, s4, 31
	v_ashrrev_i32_e32 v151, 31, v150
	v_lshl_add_u32 v22, v1, 4, v0
	v_mul_lo_u32 v0, v154, s89
	v_bitop3_b32 v1, v154, v3, 7 bitop3:0x6c
	v_lshl_add_u64 v[10:11], v[150:151], 0, s[4:5]
	v_mov_b64_e32 v[52:53], s[2:3]
	v_lshlrev_b32_e32 v16, 3, v3
	v_lshl_add_u32 v23, v1, 4, v0
	v_lshlrev_b32_e32 v0, 3, v66
	v_and_b32_e32 v1, 0xc0, v67
	v_lshlrev_b32_e32 v3, 1, v41
	v_ashrrev_i32_e32 v9, 31, v8
	v_mad_u64_u32 v[14:15], s[18:19], v10, s87, v[52:53]
	v_and_or_b32 v1, v0, 24, v1
	v_and_b32_e32 v3, 32, v3
	v_and_b32_e32 v0, 0x100, v0
	v_mad_i32_i24 v15, v11, s87, v15
	v_lshlrev_b64 v[50:51], 1, v[8:9]
	v_ashrrev_i32_e32 v153, 31, v152
	v_or3_b32 v58, v1, v3, v0
	v_lshl_add_u64 v[0:1], v[148:149], 0, s[4:5]
	v_lshl_add_u64 v[8:9], v[14:15], 0, v[50:51]
	v_lshl_add_u64 v[14:15], v[152:153], 0, s[4:5]
	v_lshlrev_b64 v[0:1], 11, v[0:1]
	v_ashrrev_i32_e32 v13, 31, v12
	v_mad_u64_u32 v[24:25], s[18:19], v14, s87, v[52:53]
	v_lshl_add_u64 v[0:1], s[6:7], 0, v[0:1]
	v_lshlrev_b32_e32 v48, 1, v2
	v_mad_i32_i24 v25, v15, s87, v25
	v_lshlrev_b64 v[54:55], 1, v[12:13]
	v_ashrrev_i32_e32 v155, 31, v154
	v_lshl_add_u64 v[0:1], v[0:1], 0, v[48:49]
	v_lshl_add_u64 v[4:5], v[156:157], 0, s[4:5]
	v_lshl_add_u64 v[12:13], v[24:25], 0, v[54:55]
	v_lshl_add_u64 v[24:25], v[154:155], 0, s[4:5]
	global_load_dwordx4 v[0:3], v[0:1], off
	v_lshlrev_b64 v[4:5], 11, v[4:5]
	v_ashrrev_i32_e32 v17, 31, v16
	v_mad_u64_u32 v[26:27], s[18:19], v24, s87, v[52:53]
	v_lshl_add_u64 v[4:5], s[6:7], 0, v[4:5]
	v_mad_i32_i24 v27, v25, s87, v27
	v_lshlrev_b64 v[56:57], 1, v[16:17]
	v_lshl_add_u64 v[4:5], v[4:5], 0, v[48:49]
	v_lshl_add_u64 v[16:17], v[26:27], 0, v[56:57]
	global_load_dwordx4 v[4:7], v[4:5], off
	v_add_u32_e32 v182, 0, v19
	global_load_dwordx4 v[8:11], v[8:9], off
	v_and_b32_e32 v72, 0x70, v18
	global_load_dwordx4 v[12:15], v[12:13], off
	v_add_u32_e32 v183, 0, v20
	global_load_dwordx4 v[24:27], v[16:17], off
	s_waitcnt vmcnt(0)
	v_add_u32_e32 v184, 0, v21
	v_add_u32_e32 v185, 0, v22
	v_add_u32_e32 v186, 0, v23
	v_bitop3_b32 v60, v65, v59, v72 bitop3:0xde
	v_add_u32_e32 v189, 0, v60
	s_movk_i32 s5, 0x80
	s_mov_b32 s44, s45
	v_add_u32_e32 v172, s16, v58
	v_lshl_add_u64 v[160:161], s[6:7], 0, v[48:49]
	v_lshl_add_u64 v[162:163], s[2:3], 0, v[50:51]
	v_lshl_add_u64 v[164:165], s[2:3], 0, v[54:55]
	v_lshl_add_u64 v[166:167], s[2:3], 0, v[56:57]
	v_cmp_gt_u32_e64 s[2:3], 32, v66
	s_waitcnt vmcnt(4)
	ds_write_b128 v182, v[0:3]
	v_mov_b32_e32 v0, 0x3000
	v_mad_u32_u24 v71, v168, s89, v0
	v_bitop3_b32 v0, v176, v59, v72 bitop3:0xde
	v_add_u32_e32 v187, 0, v0
	v_bitop3_b32 v67, v65, v71, v72 bitop3:0xde
	v_bitop3_b32 v64, v176, v71, v72 bitop3:0xde
	v_add_u32_e32 v202, 0, v64
	v_add_u32_e32 v201, 0, v67
	s_waitcnt vmcnt(3)
	ds_write_b128 v183, v[4:7]
	s_waitcnt vmcnt(2)
	ds_write_b128 v184, v[8:11] offset:32768
	s_waitcnt vmcnt(1)
	ds_write_b128 v185, v[12:15] offset:32768
	v_mov_b64_e32 v[0:1], s[44:45]
	s_waitcnt vmcnt(0)
	ds_write_b128 v186, v[24:27] offset:32768
	s_waitcnt lgkmcnt(0)
	s_barrier
	ds_read_b128 v[16:19], v187 offset:32768
	ds_read_b128 v[20:23], v187 offset:45056
	ds_read_b128 v[60:63], v189 offset:32768
	ds_read_b128 v[74:77], v189 offset:45056
	s_waitcnt lgkmcnt(3)
	v_mfma_f32_32x32x16_bf16 v[32:47], v[16:19], v[96:99], 0
	v_mov_b64_e32 v[14:15], s[58:59]
	v_mov_b64_e32 v[2:3], s[46:47]
	v_mov_b64_e32 v[4:5], s[48:49]
	v_mov_b64_e32 v[6:7], s[50:51]
	v_mov_b64_e32 v[8:9], s[52:53]
	v_mov_b64_e32 v[10:11], s[54:55]
	v_mov_b64_e32 v[12:13], s[56:57]
	s_waitcnt lgkmcnt(2)
	v_mfma_f32_32x32x16_bf16 v[16:31], v[20:23], v[96:99], 0
	s_waitcnt lgkmcnt(1)
	v_mfma_f32_32x32x16_bf16 v[32:47], v[60:63], v[100:103], v[32:47]
	v_or_b32_e32 v60, 64, v176
	v_bitop3_b32 v61, v60, v59, v72 bitop3:0xde
	v_add_u32_e32 v190, 0, v61
	ds_read_b128 v[78:81], v190 offset:45056
	v_bitop3_b32 v61, v60, v71, v72 bitop3:0xde
	v_or_b32_e32 v60, 0x60, v176
	v_bitop3_b32 v59, v60, v59, v72 bitop3:0xde
	s_waitcnt lgkmcnt(1)
	v_mfma_f32_32x32x16_bf16 v[16:31], v[74:77], v[100:103], v[16:31]
	ds_read_b128 v[74:77], v190 offset:32768
	v_add_u32_e32 v191, 0, v59
	v_bitop3_b32 v59, v60, v71, v72 bitop3:0xde
	v_bitop3_b32 v60, v176, v72, s5 bitop3:0x36
	v_mad_u32_u24 v62, v168, s89, v60
	v_add_u32_e32 v192, 0, v62
	s_movk_i32 s5, 0xa0
	s_waitcnt lgkmcnt(0)
	v_mfma_f32_32x32x16_bf16 v[32:47], v[74:77], v[104:107], v[32:47]
	ds_read_b128 v[74:77], v191 offset:32768
	v_bitop3_b32 v62, v176, v72, s5 bitop3:0x36
	v_mad_u32_u24 v63, v168, s89, v62
	v_add_u32_e32 v193, 0, v63
	s_movk_i32 s5, 0xc0
	v_bitop3_b32 v63, v176, v72, s5 bitop3:0x36
	v_mad_u32_u24 v65, v168, s89, v63
	v_mfma_f32_32x32x16_bf16 v[16:31], v[78:81], v[104:107], v[16:31]
	ds_read_b128 v[78:81], v191 offset:45056
	v_add_u32_e32 v194, 0, v65
	s_movk_i32 s5, 0xe0
	v_bitop3_b32 v65, v176, v72, s5 bitop3:0x36
	v_mad_u32_u24 v68, v168, s89, v65
	v_add_u32_e32 v195, 0, v68
	s_movk_i32 s5, 0x100
	s_waitcnt lgkmcnt(1)
	v_mfma_f32_32x32x16_bf16 v[32:47], v[74:77], v[108:111], v[32:47]
	ds_read_b128 v[74:77], v192 offset:32768
	v_bitop3_b32 v68, v176, v72, s5 bitop3:0x36
	v_mad_u32_u24 v69, v168, s89, v68
	v_add_u32_e32 v196, 0, v69
	s_movk_i32 s5, 0x120
	v_bitop3_b32 v69, v176, v72, s5 bitop3:0x36
	v_mad_u32_u24 v70, v168, s89, v69
	s_waitcnt lgkmcnt(1)
	v_mfma_f32_32x32x16_bf16 v[16:31], v[78:81], v[108:111], v[16:31]
	ds_read_b128 v[78:81], v192 offset:45056
	v_add_u32_e32 v197, 0, v70
	s_movk_i32 s5, 0x140
	v_bitop3_b32 v70, v176, v72, s5 bitop3:0x36
	v_mad_u32_u24 v73, v168, s89, v70
	v_add_u32_e32 v199, 0, v73
	s_movk_i32 s5, 0x160
	s_waitcnt lgkmcnt(1)
	v_mfma_f32_32x32x16_bf16 v[32:47], v[74:77], v[112:115], v[32:47]
	ds_read_b128 v[74:77], v193 offset:32768
	v_add_u32_e32 v60, v60, v71
	v_add_u32_e32 v62, v62, v71
	v_add_u32_e32 v63, v63, v71
	v_add_u32_e32 v65, v65, v71
	v_add_u32_e32 v68, v68, v71
	v_add_u32_e32 v69, v69, v71
	s_waitcnt lgkmcnt(1)
	v_mfma_f32_32x32x16_bf16 v[16:31], v[78:81], v[112:115], v[16:31]
	ds_read_b128 v[78:81], v193 offset:45056
	v_add_u32_e32 v70, v70, v71
	v_add_u32_e32 v209, 0, v61
	v_add_u32_e32 v212, 0, v59
	v_add_u32_e32 v211, 0, v60
	v_add_u32_e32 v210, 0, v62
	v_add_u32_e32 v208, 0, v63
	s_waitcnt lgkmcnt(1)
	v_mfma_f32_32x32x16_bf16 v[32:47], v[74:77], v[116:119], v[32:47]
	ds_read_b128 v[74:77], v194 offset:32768
	v_add_u32_e32 v207, 0, v65
	v_add_u32_e32 v206, 0, v68
	v_add_u32_e32 v205, 0, v69
	v_add_u32_e32 v204, 0, v70
	s_waitcnt lgkmcnt(1)
	v_mfma_f32_32x32x16_bf16 v[16:31], v[78:81], v[116:119], v[16:31]
	ds_read_b128 v[78:81], v194 offset:45056
	ds_read_b128 v[82:85], v171
	s_waitcnt lgkmcnt(0)
	v_mfma_f32_32x32x16_bf16 v[32:47], v[74:77], v[82:85], v[32:47]
	ds_read_b128 v[74:77], v195 offset:32768
	v_mfma_f32_32x32x16_bf16 v[16:31], v[78:81], v[82:85], v[16:31]
	ds_read_b128 v[78:81], v195 offset:45056
	ds_read_b128 v[82:85], v171 offset:1024
	s_waitcnt lgkmcnt(0)
	v_mfma_f32_32x32x16_bf16 v[32:47], v[74:77], v[82:85], v[32:47]
	ds_read_b128 v[74:77], v196 offset:32768
	v_mfma_f32_32x32x16_bf16 v[16:31], v[78:81], v[82:85], v[16:31]
	ds_read_b128 v[78:81], v196 offset:45056
	ds_read_b128 v[82:85], v171 offset:2048
	s_waitcnt lgkmcnt(0)
	v_mfma_f32_32x32x16_bf16 v[32:47], v[74:77], v[82:85], v[32:47]
	ds_read_b128 v[74:77], v197 offset:32768
	v_mfma_f32_32x32x16_bf16 v[16:31], v[78:81], v[82:85], v[16:31]
	ds_read_b128 v[78:81], v197 offset:45056
	ds_read_b128 v[82:85], v171 offset:3072
	s_waitcnt lgkmcnt(0)
	v_mfma_f32_32x32x16_bf16 v[32:47], v[74:77], v[82:85], v[32:47]
	ds_read_b128 v[74:77], v199 offset:32768
	v_mfma_f32_32x32x16_bf16 v[16:31], v[78:81], v[82:85], v[16:31]
	ds_read_b128 v[78:81], v199 offset:45056
	ds_read_b128 v[82:85], v171 offset:4096
	s_waitcnt lgkmcnt(0)
	v_mfma_f32_32x32x16_bf16 v[32:47], v[74:77], v[82:85], v[32:47]
	v_bitop3_b32 v76, v176, v72, s5 bitop3:0x36
	v_mad_u32_u24 v72, v168, s89, v76
	v_add_u32_e32 v198, 0, v72
	ds_read_b128 v[72:75], v198 offset:32768
	v_add_u32_e32 v71, v76, v71
	v_add_u32_e32 v203, 0, v71
	v_mfma_f32_32x32x16_bf16 v[16:31], v[78:81], v[82:85], v[16:31]
	ds_read_b128 v[76:79], v198 offset:45056
	ds_read_b128 v[80:83], v171 offset:5120
	s_waitcnt lgkmcnt(0)
	v_mfma_f32_32x32x16_bf16 v[32:47], v[72:75], v[80:83], v[32:47]
	v_mov_b32_e32 v74, 0xf149f2ca
	v_mfma_f32_32x32x16_bf16 v[16:31], v[76:79], v[80:83], v[16:31]
	s_nop 9
	v_max_f32_e32 v72, v33, v33
	v_max_f32_e32 v73, v32, v32
	v_max_f32_e32 v72, v73, v72
	v_max3_f32 v72, v72, v34, v35
	v_max3_f32 v72, v72, v36, v37
	v_max3_f32 v72, v72, v38, v39
	v_max3_f32 v72, v72, v40, v41
	v_max3_f32 v72, v72, v42, v43
	v_max3_f32 v72, v72, v44, v45
	v_max3_f32 v72, v72, v46, v47
	v_max3_f32 v72, v72, v16, v17
	v_max3_f32 v72, v72, v18, v19
	v_max3_f32 v72, v72, v20, v21
	v_max3_f32 v72, v72, v22, v23
	v_max3_f32 v72, v72, v24, v25
	v_max3_f32 v72, v72, v26, v27
	v_max3_f32 v72, v72, v28, v29
	v_max3_f32 v72, v72, v30, v31
	v_mov_b32_e32 v73, v72
	s_nop 1
	v_permlane32_swap_b32_e32 v72, v73
	v_max_f32_e32 v73, v73, v73
	v_max_f32_e32 v72, v72, v72
	v_max_f32_e32 v72, v72, v73
	v_add_f32_e32 v73, 0x7149f2ca, v72
	v_cmp_ge_f32_e32 vcc, s90, v73
	s_cmp_eq_u64 vcc, exec
	s_cselect_b64 vcc, -1, 0
	v_max_f32_e32 v72, 0xf149f2ca, v72
	s_add_i32 s18, s15, 0x8040
	v_cndmask_b32_e32 v158, v72, v74, vcc
	s_ashr_i32 s19, s18, 31
	v_sub_f32_e32 v132, v16, v158
	v_sub_f32_e32 v133, v17, v158
	v_lshl_add_u64 v[16:17], v[148:149], 0, s[18:19]
	v_sub_f32_e32 v124, v20, v158
	v_sub_f32_e32 v125, v21, v158
	v_lshlrev_b64 v[16:17], 11, v[16:17]
	v_lshl_add_u64 v[20:21], v[156:157], 0, s[18:19]
	v_sub_f32_e32 v128, v24, v158
	v_sub_f32_e32 v129, v25, v158
	v_lshl_add_u64 v[16:17], s[6:7], 0, v[16:17]
	v_lshlrev_b64 v[20:21], 11, v[20:21]
	v_lshl_add_u64 v[24:25], v[150:151], 0, s[18:19]
	v_sub_f32_e32 v32, v32, v158
	v_sub_f32_e32 v33, v33, v158
	v_sub_f32_e32 v130, v26, v158
	v_sub_f32_e32 v131, v27, v158
	v_sub_f32_e32 v120, v28, v158
	v_sub_f32_e32 v121, v29, v158
	v_lshl_add_u64 v[16:17], v[16:17], 0, v[48:49]
	v_lshl_add_u64 v[20:21], s[6:7], 0, v[20:21]
	v_mad_u64_u32 v[26:27], s[20:21], v24, s87, v[52:53]
	v_lshl_add_u64 v[28:29], v[152:153], 0, s[18:19]
	v_sub_f32_e32 v34, v34, v158
	v_sub_f32_e32 v35, v35, v158
	v_sub_f32_e32 v134, v18, v158
	v_sub_f32_e32 v135, v19, v158
	v_sub_f32_e32 v122, v30, v158
	v_sub_f32_e32 v123, v31, v158
	v_exp_f32_e32 v136, v32
	v_exp_f32_e32 v230, v33
	global_load_dwordx4 v[16:19], v[16:17], off
	v_lshl_add_u64 v[20:21], v[20:21], 0, v[48:49]
	v_mad_i32_i24 v27, v25, s87, v27
	v_mad_u64_u32 v[30:31], s[20:21], v28, s87, v[52:53]
	v_lshl_add_u64 v[32:33], v[154:155], 0, s[18:19]
	v_sub_f32_e32 v126, v22, v158
	v_sub_f32_e32 v127, v23, v158
	v_exp_f32_e32 v137, v34
	v_exp_f32_e32 v229, v35
	global_load_dwordx4 v[20:23], v[20:21], off
	v_lshl_add_u64 v[24:25], v[26:27], 0, v[50:51]
	v_mad_i32_i24 v31, v29, s87, v31
	v_mad_u64_u32 v[34:35], s[18:19], v32, s87, v[52:53]
	global_load_dwordx4 v[24:27], v[24:25], off
	v_lshl_add_u64 v[28:29], v[30:31], 0, v[54:55]
	v_mad_i32_i24 v35, v33, s87, v35
	global_load_dwordx4 v[28:31], v[28:29], off
	v_lshl_add_u64 v[32:33], v[34:35], 0, v[56:57]
	global_load_dwordx4 v[32:35], v[32:33], off
	v_sub_f32_e32 v73, 0xf149f2ca, v72
	v_exp_f32_e32 v73, v73
	v_sub_f32_e32 v36, v36, v158
	v_sub_f32_e32 v37, v37, v158
	v_sub_f32_e32 v38, v38, v158
	v_sub_f32_e32 v39, v39, v158
	v_sub_f32_e32 v40, v40, v158
	v_sub_f32_e32 v41, v41, v158
	v_sub_f32_e32 v42, v42, v158
	v_sub_f32_e32 v43, v43, v158
	v_sub_f32_e32 v44, v44, v158
	v_sub_f32_e32 v45, v45, v158
	v_sub_f32_e32 v46, v46, v158
	v_sub_f32_e32 v47, v47, v158
	v_exp_f32_e32 v138, v36
	v_exp_f32_e32 v228, v37
	v_exp_f32_e32 v139, v38
	v_exp_f32_e32 v213, v39
	v_exp_f32_e32 v144, v40
	v_exp_f32_e32 v147, v41
	v_exp_f32_e32 v145, v42
	v_exp_f32_e32 v146, v43
	v_exp_f32_e32 v141, v44
	v_exp_f32_e32 v143, v45
	v_exp_f32_e32 v140, v46
	v_exp_f32_e32 v142, v47
	s_waitcnt vmcnt(0)
	s_addk_i32 s16, 0x4000
	s_waitcnt vmcnt(4)
	ds_write_b128 v182, v[16:19] offset:16384
	s_waitcnt vmcnt(3)
	ds_write_b128 v183, v[20:23] offset:16384
	s_waitcnt vmcnt(2)
	ds_write_b128 v184, v[24:27] offset:57344
	s_waitcnt vmcnt(1)
	ds_write_b128 v185, v[28:31] offset:57344
	s_waitcnt vmcnt(0)
	ds_write_b128 v186, v[32:35] offset:57344
	v_add_u32_e32 v175, s16, v58
	v_mov_b64_e32 v[46:47], v[14:15]
	v_mov_b64_e32 v[30:31], v[14:15]
	v_mov_b64_e32 v[62:63], v[14:15]
	v_cndmask_b32_e64 v200, v73, 1.0, vcc
	s_add_i32 s15, s4, 0x80
	s_sub_i32 s14, s14, 64
	v_mov_b64_e32 v[44:45], v[12:13]
	v_mov_b64_e32 v[42:43], v[10:11]
	v_mov_b64_e32 v[40:41], v[8:9]
	v_mov_b64_e32 v[38:39], v[6:7]
	v_mov_b64_e32 v[36:37], v[4:5]
	v_mov_b64_e32 v[34:35], v[2:3]
	v_mov_b64_e32 v[32:33], v[0:1]
	v_mov_b64_e32 v[28:29], v[12:13]
	v_mov_b64_e32 v[26:27], v[10:11]
	v_mov_b64_e32 v[24:25], v[8:9]
	v_mov_b64_e32 v[22:23], v[6:7]
	v_mov_b64_e32 v[20:21], v[4:5]
	v_mov_b64_e32 v[18:19], v[2:3]
	v_mov_b64_e32 v[16:17], v[0:1]
	v_mov_b64_e32 v[60:61], v[12:13]
	v_mov_b64_e32 v[58:59], v[10:11]
	v_mov_b64_e32 v[56:57], v[8:9]
	v_mov_b64_e32 v[54:55], v[6:7]
	v_mov_b64_e32 v[52:53], v[4:5]
	v_mov_b64_e32 v[50:51], v[2:3]
	v_mov_b64_e32 v[48:49], v[0:1]
	s_waitcnt lgkmcnt(0)
	s_barrier
	v_lshlrev_b64 v[148:149], 11, v[148:149]
	v_lshlrev_b64 v[156:157], 11, v[156:157]
	v_lshl_add_u64 v[148:149], v[160:161], 0, v[148:149]
	v_lshl_add_u64 v[156:157], v[160:161], 0, v[156:157]
	v_mad_u64_u32 v[150:151], s[74:75], v150, s87, v[162:163]
	v_mad_u64_u32 v[152:153], s[74:75], v152, s87, v[164:165]
	v_mad_u64_u32 v[154:155], s[74:75], v154, s87, v[166:167]
	v_readfirstlane_b32 s21, v181
	s_nop 3
	s_lshr_b32 s21, s21, 6
	s_cmp_ge_u32 s21, 4
	s_cbranch_scc0 .Lattn_prio_done
	s_setprio 1
.Lattn_prio_done:
.LBB0_563:
	s_add_i32 s16, s13, -1
	ds_read_b128 v[64:67], v187 offset:57344
	ds_read_b128 v[68:71], v202 offset:57344
	ds_read_b128 v[220:223], v189 offset:57344
	ds_read_b128 v[232:235], v201 offset:57344
	v_add_f32_e32 v178, 0, v136
	v_add_f32_e32 v178, v230, v178
	s_waitcnt lgkmcnt(3)
	v_mfma_f32_32x32x16_bf16 v[80:95], v[64:67], v[96:99], 0
	v_add_f32_e32 v178, v137, v178
	v_add_f32_e32 v178, v229, v178
	v_add_f32_e32 v178, v138, v178
	v_add_f32_e32 v178, v228, v178
	v_add_f32_e32 v178, v139, v178
	v_add_f32_e32 v178, v213, v178
	v_add_f32_e32 v178, v144, v178
	s_waitcnt lgkmcnt(2)
	v_mfma_f32_32x32x16_bf16 v[64:79], v[68:71], v[96:99], 0
	v_add_f32_e32 v178, v147, v178
	v_add_f32_e32 v178, v145, v178
	v_add_f32_e32 v178, v146, v178
	v_exp_f32_e32 v132, v132
	v_add_f32_e32 v178, v141, v178
	v_exp_f32_e32 v133, v133
	v_add_f32_e32 v178, v143, v178
	s_waitcnt lgkmcnt(1)
	v_mfma_f32_32x32x16_bf16 v[80:95], v[220:223], v[100:103], v[80:95]
	v_exp_f32_e32 v134, v134
	v_add_f32_e32 v178, v140, v178
	v_exp_f32_e32 v135, v135
	v_add_f32_e32 v178, v142, v178
	v_exp_f32_e32 v124, v124
	v_add_f32_e32 v178, v132, v178
	v_exp_f32_e32 v125, v125
	s_waitcnt lgkmcnt(0)
	v_mfma_f32_32x32x16_bf16 v[64:79], v[232:235], v[100:103], v[64:79]
	ds_read_b128 v[220:223], v190 offset:57344
	ds_read_b128 v[232:235], v209 offset:57344
	v_add_f32_e32 v178, v133, v178
	v_exp_f32_e32 v126, v126
	v_add_f32_e32 v178, v134, v178
	v_exp_f32_e32 v127, v127
	v_add_f32_e32 v178, v135, v178
	v_exp_f32_e32 v128, v128
	s_waitcnt lgkmcnt(1)
	v_mfma_f32_32x32x16_bf16 v[80:95], v[220:223], v[104:107], v[80:95]
	v_add_f32_e32 v178, v124, v178
	v_exp_f32_e32 v129, v129
	v_add_f32_e32 v178, v125, v178
	v_exp_f32_e32 v130, v130
	v_add_f32_e32 v178, v126, v178
	v_exp_f32_e32 v131, v131
	v_add_f32_e32 v178, v127, v178
	s_waitcnt lgkmcnt(0)
	v_mfma_f32_32x32x16_bf16 v[64:79], v[232:235], v[104:107], v[64:79]
	ds_read_b128 v[220:223], v191 offset:57344
	ds_read_b128 v[232:235], v212 offset:57344
	v_exp_f32_e32 v120, v120
	v_add_f32_e32 v178, v128, v178
	v_exp_f32_e32 v121, v121
	v_add_f32_e32 v178, v129, v178
	v_exp_f32_e32 v122, v122
	v_add_f32_e32 v178, v130, v178
	s_waitcnt lgkmcnt(1)
	v_mfma_f32_32x32x16_bf16 v[80:95], v[220:223], v[108:111], v[80:95]
	v_exp_f32_e32 v123, v123
	v_add_f32_e32 v178, v131, v178
	v_add_f32_e32 v178, v120, v178
	v_add_f32_e32 v178, v121, v178
	v_add_f32_e32 v178, v122, v178
	v_add_f32_e32 v231, v123, v178
	s_waitcnt lgkmcnt(0)
	v_mfma_f32_32x32x16_bf16 v[64:79], v[232:235], v[108:111], v[64:79]
	ds_read_b128 v[220:223], v192 offset:57344
	ds_read_b128 v[232:235], v211 offset:57344
	s_waitcnt lgkmcnt(1)
	v_mfma_f32_32x32x16_bf16 v[80:95], v[220:223], v[112:115], v[80:95]
	s_waitcnt lgkmcnt(0)
	v_mfma_f32_32x32x16_bf16 v[64:79], v[232:235], v[112:115], v[64:79]
	ds_read_b128 v[220:223], v193 offset:57344
	ds_read_b128 v[232:235], v210 offset:57344
	s_waitcnt lgkmcnt(1)
	v_mfma_f32_32x32x16_bf16 v[80:95], v[220:223], v[116:119], v[80:95]
	s_waitcnt lgkmcnt(0)
	v_mfma_f32_32x32x16_bf16 v[64:79], v[232:235], v[116:119], v[64:79]
	ds_read_b128 v[220:223], v194 offset:57344
	ds_read_b128 v[232:235], v208 offset:57344
	ds_read_b128 v[236:239], v171
	s_waitcnt lgkmcnt(0)
	v_mfma_f32_32x32x16_bf16 v[80:95], v[220:223], v[236:239], v[80:95]
	v_mfma_f32_32x32x16_bf16 v[64:79], v[232:235], v[236:239], v[64:79]
	ds_read_b128 v[220:223], v195 offset:57344
	ds_read_b128 v[232:235], v207 offset:57344
	ds_read_b128 v[236:239], v171 offset:1024
	s_waitcnt lgkmcnt(0)
	v_mfma_f32_32x32x16_bf16 v[80:95], v[220:223], v[236:239], v[80:95]
	v_mfma_f32_32x32x16_bf16 v[64:79], v[232:235], v[236:239], v[64:79]
	ds_read_b128 v[220:223], v196 offset:57344
	ds_read_b128 v[232:235], v206 offset:57344
	ds_read_b128 v[236:239], v171 offset:2048
	s_waitcnt lgkmcnt(0)
	v_mfma_f32_32x32x16_bf16 v[80:95], v[220:223], v[236:239], v[80:95]
	v_mfma_f32_32x32x16_bf16 v[64:79], v[232:235], v[236:239], v[64:79]
	ds_read_b128 v[220:223], v197 offset:57344
	ds_read_b128 v[232:235], v205 offset:57344
	ds_read_b128 v[236:239], v171 offset:3072
	s_waitcnt lgkmcnt(0)
	v_mfma_f32_32x32x16_bf16 v[80:95], v[220:223], v[236:239], v[80:95]
	v_mfma_f32_32x32x16_bf16 v[64:79], v[232:235], v[236:239], v[64:79]
	ds_read_b128 v[220:223], v199 offset:57344
	ds_read_b128 v[232:235], v204 offset:57344
	ds_read_b128 v[236:239], v171 offset:4096
	s_waitcnt lgkmcnt(0)
	v_mfma_f32_32x32x16_bf16 v[80:95], v[220:223], v[236:239], v[80:95]
	v_mfma_f32_32x32x16_bf16 v[64:79], v[232:235], v[236:239], v[64:79]
	ds_read_b128 v[220:223], v198 offset:57344
	ds_read_b128 v[232:235], v203 offset:57344
	ds_read_b128 v[236:239], v171 offset:5120
	v_cvt_pk_bf16_f32 v136, v136, v230
	v_cvt_pk_bf16_f32 v137, v137, v229
	v_cvt_pk_bf16_f32 v138, v138, v228
	v_cvt_pk_bf16_f32 v139, v139, v213
	v_cvt_pk_bf16_f32 v144, v144, v147
	v_cvt_pk_bf16_f32 v145, v145, v146
	s_waitcnt lgkmcnt(0)
	v_mfma_f32_32x32x16_bf16 v[80:95], v[220:223], v[236:239], v[80:95]
	v_cvt_pk_bf16_f32 v146, v141, v143
	v_cvt_pk_bf16_f32 v147, v140, v142
	v_cvt_pk_bf16_f32 v220, v132, v133
	v_cvt_pk_bf16_f32 v221, v134, v135
	v_cvt_pk_bf16_f32 v222, v124, v125
	v_cvt_pk_bf16_f32 v223, v126, v127
	v_permlane32_swap_b32_e32 v136, v138
	v_mfma_f32_32x32x16_bf16 v[64:79], v[232:235], v[236:239], v[64:79]
	v_mov_b32_e32 v233, v231
	v_cvt_pk_bf16_f32 v234, v128, v129
	v_cvt_pk_bf16_f32 v235, v130, v131
	v_cvt_pk_bf16_f32 v236, v120, v121
	s_nop 1
	v_permlane32_swap_b32_e32 v231, v233
	v_cvt_pk_bf16_f32 v237, v122, v123
	v_permlane32_swap_b32_e32 v234, v236
	v_permlane32_swap_b32_e32 v137, v139
	v_permlane32_swap_b32_e32 v144, v146
	v_permlane32_swap_b32_e32 v145, v147
	v_permlane32_swap_b32_e32 v220, v222
	v_permlane32_swap_b32_e32 v221, v223
	v_permlane32_swap_b32_e32 v235, v237
	s_sub_i32 s4, s14, 64
	s_cmp_lt_u32 s16, 3
	s_cselect_b32 s4, s15, s4
	s_ashr_i32 s5, s4, 31
	s_lshl_b64 s[76:77], s[4:5], 11
	s_mul_hi_i32 s79, s4, s87
	s_mul_i32 s78, s4, s87
	v_lshl_add_u64 v[120:121], v[148:149], 0, s[76:77]
	v_lshl_add_u64 v[124:125], v[156:157], 0, s[76:77]
	v_lshl_add_u64 v[130:131], v[150:151], 0, s[78:79]
	v_lshl_add_u64 v[134:135], v[152:153], 0, s[78:79]
	v_lshl_add_u64 v[140:141], v[154:155], 0, s[78:79]
	global_load_dwordx4 v[120:123], v[120:121], off
	global_load_dwordx4 v[124:127], v[124:125], off
	global_load_dwordx4 v[128:131], v[130:131], off
	global_load_dwordx4 v[132:135], v[134:135], off
	global_load_dwordx4 v[140:143], v[140:141], off
	ds_read_b64_tr_b16 v[238:239], v172 offset:0
	ds_read_b64_tr_b16 v[240:241], v172 offset:0x800
	ds_read_b64_tr_b16 v[242:243], v172 offset:0x1000
	ds_read_b64_tr_b16 v[244:245], v172 offset:0x1800
	ds_read_b64_tr_b16 v[246:247], v172 offset:0x2000
	ds_read_b64_tr_b16 v[248:249], v172 offset:0x2800
	ds_read_b64_tr_b16 v[250:251], v172 offset:0x3000
	ds_read_b64_tr_b16 v[252:253], v172 offset:0x3800
	s_waitcnt lgkmcnt(0)
	s_nop 0
	v_mfma_f32_32x32x16_bf16 v[0:15], v[136:139], v[238:241], v[0:15]
	ds_read_b64_tr_b16 v[238:239], v172 offset:0x200
	ds_read_b64_tr_b16 v[240:241], v172 offset:0xa00
	v_mfma_f32_32x32x16_bf16 v[0:15], v[144:147], v[242:245], v[0:15]
	ds_read_b64_tr_b16 v[242:243], v172 offset:0x1200
	ds_read_b64_tr_b16 v[244:245], v172 offset:0x1a00
	v_mfma_f32_32x32x16_bf16 v[0:15], v[220:223], v[246:249], v[0:15]
	ds_read_b64_tr_b16 v[246:247], v172 offset:0x2200
	ds_read_b64_tr_b16 v[248:249], v172 offset:0x2a00
	v_mfma_f32_32x32x16_bf16 v[0:15], v[234:237], v[250:253], v[0:15]
	ds_read_b64_tr_b16 v[250:251], v172 offset:0x3200
	ds_read_b64_tr_b16 v[252:253], v172 offset:0x3a00
	s_waitcnt lgkmcnt(0)
	v_mfma_f32_32x32x16_bf16 v[32:47], v[136:139], v[238:241], v[32:47]
	ds_read_b64_tr_b16 v[238:239], v172 offset:0x400
	ds_read_b64_tr_b16 v[240:241], v172 offset:0xc00
	v_mfma_f32_32x32x16_bf16 v[32:47], v[144:147], v[242:245], v[32:47]
	ds_read_b64_tr_b16 v[242:243], v172 offset:0x1400
	ds_read_b64_tr_b16 v[244:245], v172 offset:0x1c00
	v_mfma_f32_32x32x16_bf16 v[32:47], v[220:223], v[246:249], v[32:47]
	ds_read_b64_tr_b16 v[246:247], v172 offset:0x2400
	ds_read_b64_tr_b16 v[248:249], v172 offset:0x2c00
	v_mfma_f32_32x32x16_bf16 v[32:47], v[234:237], v[250:253], v[32:47]
	ds_read_b64_tr_b16 v[250:251], v172 offset:0x3400
	ds_read_b64_tr_b16 v[252:253], v172 offset:0x3c00
	s_waitcnt lgkmcnt(0)
	v_mfma_f32_32x32x16_bf16 v[16:31], v[136:139], v[238:241], v[16:31]
	ds_read_b64_tr_b16 v[238:239], v172 offset:0x600
	ds_read_b64_tr_b16 v[240:241], v172 offset:0xe00
	v_mfma_f32_32x32x16_bf16 v[16:31], v[144:147], v[242:245], v[16:31]
	ds_read_b64_tr_b16 v[242:243], v172 offset:0x1600
	ds_read_b64_tr_b16 v[244:245], v172 offset:0x1e00
	v_mfma_f32_32x32x16_bf16 v[16:31], v[220:223], v[246:249], v[16:31]
	ds_read_b64_tr_b16 v[246:247], v172 offset:0x2600
	ds_read_b64_tr_b16 v[248:249], v172 offset:0x2e00
	v_mfma_f32_32x32x16_bf16 v[16:31], v[234:237], v[250:253], v[16:31]
	ds_read_b64_tr_b16 v[250:251], v172 offset:0x3600
	ds_read_b64_tr_b16 v[252:253], v172 offset:0x3e00
	s_waitcnt lgkmcnt(0)
	v_mfma_f32_32x32x16_bf16 v[48:63], v[136:139], v[238:241], v[48:63]
	v_max_f32_e32 v136, v81, v81
	v_max_f32_e32 v137, v80, v80
	v_max_f32_e32 v136, v137, v136
	v_max3_f32 v136, v136, v82, v83
	v_max3_f32 v136, v136, v84, v85
	v_max3_f32 v136, v136, v86, v87
	v_max3_f32 v136, v136, v88, v89
	v_max3_f32 v136, v136, v90, v91
	v_mfma_f32_32x32x16_bf16 v[48:63], v[144:147], v[242:245], v[48:63]
	v_max3_f32 v136, v136, v92, v93
	v_max3_f32 v136, v136, v94, v95
	v_max3_f32 v136, v136, v64, v65
	v_max3_f32 v136, v136, v66, v67
	v_max3_f32 v136, v136, v68, v69
	v_max3_f32 v136, v136, v70, v71
	v_max3_f32 v136, v136, v72, v73
	v_max3_f32 v136, v136, v74, v75
	v_mfma_f32_32x32x16_bf16 v[48:63], v[220:223], v[246:249], v[48:63]
	v_max3_f32 v136, v136, v76, v77
	v_max3_f32 v136, v136, v78, v79
	v_mov_b32_e32 v137, v136
	s_nop 1
	v_permlane32_swap_b32_e32 v136, v137
	v_max_f32_e32 v137, v137, v137
	v_max_f32_e32 v136, v136, v136
	v_max_f32_e32 v136, v136, v137
	v_sub_f32_e32 v137, v136, v158
	v_cmp_ge_f32_e32 vcc, s90, v137
	v_max_f32_e32 v137, v158, v158
	v_mfma_f32_32x32x16_bf16 v[48:63], v[234:237], v[250:253], v[48:63]
	v_max_f32_e32 v136, v137, v136
	v_sub_f32_e32 v137, v158, v136
	v_exp_f32_e32 v137, v137
	s_cmp_eq_u64 vcc, exec
	s_cselect_b64 s[4:5], -1, 0
	s_barrier
	s_waitcnt vmcnt(0)
	v_cndmask_b32_e64 v234, v137, 1.0, s[4:5]
	v_cmp_gt_f32_e32 vcc, 1.0, v234
	ds_write_b128 v182, v[120:123]
	ds_write_b128 v183, v[124:127]
	ds_write_b128 v184, v[128:131] offset:32768
	ds_write_b128 v185, v[132:135] offset:32768
	s_waitcnt vmcnt(0)
	ds_write_b128 v186, v[140:143] offset:32768
	s_cbranch_vccz .LBB0_567
	s_and_saveexec_b64 s[6:7], s[2:3]
	ds_write_b32 v173, v234 offset:128
	s_or_b64 exec, exec, s[6:7]
	s_waitcnt lgkmcnt(0)
	v_add_u32_e32 v132, v169, v176
	ds_read_b128 v[120:123], v132 offset:224
	ds_read_b128 v[124:127], v132 offset:192
	ds_read_b128 v[128:131], v132 offset:160
	ds_read_b128 v[132:135], v132 offset:128
	s_waitcnt lgkmcnt(3)
	v_pk_mul_f32 v[12:13], v[12:13], v[120:121]
	s_waitcnt lgkmcnt(2)
	v_pk_mul_f32 v[8:9], v[8:9], v[124:125]
	s_waitcnt lgkmcnt(1)
	v_pk_mul_f32 v[4:5], v[4:5], v[128:129]
	v_pk_mul_f32 v[14:15], v[14:15], v[122:123]
	v_pk_mul_f32 v[10:11], v[10:11], v[126:127]
	v_pk_mul_f32 v[6:7], v[6:7], v[130:131]
	s_waitcnt lgkmcnt(0)
	v_pk_mul_f32 v[2:3], v[2:3], v[134:135]
	v_pk_mul_f32 v[0:1], v[0:1], v[132:133]
	v_pk_mul_f32 v[44:45], v[44:45], v[120:121]
	v_pk_mul_f32 v[40:41], v[40:41], v[124:125]
	v_pk_mul_f32 v[36:37], v[36:37], v[128:129]
	v_pk_mul_f32 v[46:47], v[46:47], v[122:123]
	v_pk_mul_f32 v[42:43], v[42:43], v[126:127]
	v_pk_mul_f32 v[38:39], v[38:39], v[130:131]
	v_pk_mul_f32 v[34:35], v[34:35], v[134:135]
	v_pk_mul_f32 v[32:33], v[32:33], v[132:133]
	v_pk_mul_f32 v[28:29], v[28:29], v[120:121]
	v_pk_mul_f32 v[24:25], v[24:25], v[124:125]
	v_pk_mul_f32 v[20:21], v[20:21], v[128:129]
	v_pk_mul_f32 v[30:31], v[30:31], v[122:123]
	v_pk_mul_f32 v[26:27], v[26:27], v[126:127]
	v_pk_mul_f32 v[22:23], v[22:23], v[130:131]
	v_pk_mul_f32 v[18:19], v[18:19], v[134:135]
	v_pk_mul_f32 v[16:17], v[16:17], v[132:133]
	v_pk_mul_f32 v[60:61], v[60:61], v[120:121]
	v_pk_mul_f32 v[56:57], v[56:57], v[124:125]
	v_pk_mul_f32 v[52:53], v[52:53], v[128:129]
	v_pk_mul_f32 v[62:63], v[62:63], v[122:123]
	v_pk_mul_f32 v[58:59], v[58:59], v[126:127]
	v_pk_mul_f32 v[54:55], v[54:55], v[130:131]
	v_pk_mul_f32 v[50:51], v[50:51], v[134:135]
	v_pk_mul_f32 v[48:49], v[48:49], v[132:133]
